# residual-GEMM epilogues: first-half residual quads prefetched inside the K loop (iteration last-1) into spare registers
# speedup vs baseline: 1.0087x; 1.0003x over previous
.LBB0_1062:
	ds_read_b128 v[128:131], v189
	ds_read_b128 v[132:135], v189 offset:1024
	ds_read_b128 v[136:139], v189 offset:2048
	ds_read_b128 v[140:143], v189 offset:3072
	s_add_u32 s52, s50, 0xfff00080
	s_addc_u32 s53, s51, -1
	s_cmp_eq_u32 s60, 60
	s_cselect_b32 s55, s27, s53
	s_cselect_b32 s54, s37, s52
	s_cselect_b32 s53, s25, s59
	s_cselect_b32 s52, s57, s58
	v_lshl_add_u64 v[184:185], s[50:51], 0, v[160:161]
	s_add_i32 m0, s34, 0xc000
	ds_read_b128 v[144:147], v190
	ds_read_b128 v[148:151], v190 offset:1024
	ds_read_b128 v[168:171], v190 offset:2048
	ds_read_b128 v[172:175], v190 offset:3072
	ds_read_b128 v[176:179], v190 offset:4096
	ds_read_b128 v[180:183], v190 offset:5120
	ds_read_b128 v[192:195], v190 offset:6144
	ds_read_b128 v[196:199], v190 offset:7168
	global_load_lds_dwordx4 v[184:185], off
	v_lshl_add_u64 v[184:185], s[50:51], 0, v[162:163]
	s_add_i32 m0, s34, 0xe000
	s_nop 0
	global_load_lds_dwordx4 v[184:185], off
	s_waitcnt lgkmcnt(8)
	s_barrier
	s_waitcnt lgkmcnt(0)
	s_setprio 1
	s_waitcnt lgkmcnt(0)
	v_mfma_f32_16x16x32_bf16 v[124:127], v[128:131], v[144:147], v[124:127]
	v_mfma_f32_16x16x32_bf16 v[120:123], v[136:139], v[144:147], v[120:123]
	v_mfma_f32_16x16x32_bf16 v[108:111], v[128:131], v[168:171], v[108:111]
	v_mfma_f32_16x16x32_bf16 v[104:107], v[136:139], v[168:171], v[104:107]
	v_mfma_f32_16x16x32_bf16 v[92:95], v[128:131], v[176:179], v[92:95]
	v_mfma_f32_16x16x32_bf16 v[88:91], v[136:139], v[176:179], v[88:91]
	v_mfma_f32_16x16x32_bf16 v[76:79], v[128:131], v[192:195], v[76:79]
	v_mfma_f32_16x16x32_bf16 v[72:75], v[136:139], v[192:195], v[72:75]
	v_mfma_f32_16x16x32_bf16 v[124:127], v[132:135], v[148:151], v[124:127]
	v_mfma_f32_16x16x32_bf16 v[120:123], v[140:143], v[148:151], v[120:123]
	v_mfma_f32_16x16x32_bf16 v[108:111], v[132:135], v[172:175], v[108:111]
	v_mfma_f32_16x16x32_bf16 v[104:107], v[140:143], v[172:175], v[104:107]
	v_mfma_f32_16x16x32_bf16 v[92:95], v[132:135], v[180:183], v[92:95]
	v_mfma_f32_16x16x32_bf16 v[88:91], v[140:143], v[180:183], v[88:91]
	v_mfma_f32_16x16x32_bf16 v[76:79], v[132:135], v[196:199], v[76:79]
	v_mfma_f32_16x16x32_bf16 v[72:75], v[140:143], v[196:199], v[72:75]
	s_setprio 0
	s_barrier
	s_add_i32 s61, s49, s33
	v_lshl_add_u64 v[184:185], s[52:53], 0, v[154:155]
	s_mov_b32 m0, s61
	ds_read_b128 v[200:203], v191
	ds_read_b128 v[206:209], v191 offset:1024
	ds_read_b128 v[210:213], v191 offset:2048
	ds_read_b128 v[214:217], v191 offset:3072
	global_load_lds_dwordx4 v[184:185], off
	v_lshl_add_u64 v[218:219], s[52:53], 0, v[158:159]
	s_add_i32 m0, s61, 0x2000
	s_nop 0
	global_load_lds_dwordx4 v[218:219], off
	s_barrier
	s_waitcnt lgkmcnt(0)
	s_setprio 1
	s_waitcnt lgkmcnt(0)
	v_mfma_f32_16x16x32_bf16 v[116:119], v[200:203], v[144:147], v[116:119]
	v_mfma_f32_16x16x32_bf16 v[112:115], v[210:213], v[144:147], v[112:115]
	v_mfma_f32_16x16x32_bf16 v[100:103], v[200:203], v[168:171], v[100:103]
	v_mfma_f32_16x16x32_bf16 v[96:99], v[210:213], v[168:171], v[96:99]
	v_mfma_f32_16x16x32_bf16 v[84:87], v[200:203], v[176:179], v[84:87]
	v_mfma_f32_16x16x32_bf16 v[80:83], v[210:213], v[176:179], v[80:83]
	v_mfma_f32_16x16x32_bf16 v[68:71], v[200:203], v[192:195], v[68:71]
	v_mfma_f32_16x16x32_bf16 v[64:67], v[210:213], v[192:195], v[64:67]
	v_mfma_f32_16x16x32_bf16 v[116:119], v[206:209], v[148:151], v[116:119]
	v_mfma_f32_16x16x32_bf16 v[112:115], v[214:217], v[148:151], v[112:115]
	v_mfma_f32_16x16x32_bf16 v[100:103], v[206:209], v[172:175], v[100:103]
	v_mfma_f32_16x16x32_bf16 v[96:99], v[214:217], v[172:175], v[96:99]
	v_mfma_f32_16x16x32_bf16 v[84:87], v[206:209], v[180:183], v[84:87]
	v_mfma_f32_16x16x32_bf16 v[80:83], v[214:217], v[180:183], v[80:83]
	v_mfma_f32_16x16x32_bf16 v[68:71], v[206:209], v[196:199], v[68:71]
	v_mfma_f32_16x16x32_bf16 v[64:67], v[214:217], v[196:199], v[64:67]
	s_setprio 0
	s_mov_b32 m0, s34
	v_lshl_add_u64 v[220:221], s[54:55], 0, v[152:153]
	s_barrier
	ds_read_b128 v[144:147], v190 offset:16384
	ds_read_b128 v[148:151], v190 offset:17408
	ds_read_b128 v[168:171], v190 offset:18432
	ds_read_b128 v[172:175], v190 offset:19456
	ds_read_b128 v[176:179], v190 offset:20480
	ds_read_b128 v[180:183], v190 offset:21504
	ds_read_b128 v[192:195], v190 offset:22528
	ds_read_b128 v[196:199], v190 offset:23552
	global_load_lds_dwordx4 v[220:221], off
	v_lshl_add_u64 v[222:223], s[54:55], 0, v[156:157]
	s_mov_b32 m0, s35
	s_nop 0
	global_load_lds_dwordx4 v[222:223], off
	s_barrier
	s_waitcnt lgkmcnt(0)
	s_setprio 1
	s_waitcnt lgkmcnt(0)
	v_mfma_f32_16x16x32_bf16 v[60:63], v[128:131], v[144:147], v[60:63]
	v_mfma_f32_16x16x32_bf16 v[56:59], v[136:139], v[144:147], v[56:59]
	v_mfma_f32_16x16x32_bf16 v[44:47], v[128:131], v[168:171], v[44:47]
	v_mfma_f32_16x16x32_bf16 v[40:43], v[136:139], v[168:171], v[40:43]
	v_mfma_f32_16x16x32_bf16 v[28:31], v[128:131], v[176:179], v[28:31]
	v_mfma_f32_16x16x32_bf16 v[24:27], v[136:139], v[176:179], v[24:27]
	v_mfma_f32_16x16x32_bf16 v[12:15], v[128:131], v[192:195], v[12:15]
	v_mfma_f32_16x16x32_bf16 v[8:11], v[136:139], v[192:195], v[8:11]
	v_mfma_f32_16x16x32_bf16 v[60:63], v[132:135], v[148:151], v[60:63]
	v_mfma_f32_16x16x32_bf16 v[56:59], v[140:143], v[148:151], v[56:59]
	v_mfma_f32_16x16x32_bf16 v[44:47], v[132:135], v[172:175], v[44:47]
	v_mfma_f32_16x16x32_bf16 v[40:43], v[140:143], v[172:175], v[40:43]
	v_mfma_f32_16x16x32_bf16 v[28:31], v[132:135], v[180:183], v[28:31]
	v_mfma_f32_16x16x32_bf16 v[24:27], v[140:143], v[180:183], v[24:27]
	v_mfma_f32_16x16x32_bf16 v[12:15], v[132:135], v[196:199], v[12:15]
	v_mfma_f32_16x16x32_bf16 v[8:11], v[140:143], v[196:199], v[8:11]
	s_setprio 0
	s_barrier
	s_add_u32 s62, s52, 0x100000
	s_addc_u32 s63, s53, 0
	s_add_i32 s61, s56, s33
	v_lshl_add_u64 v[128:129], s[62:63], 0, v[154:155]
	s_mov_b32 m0, s61
	s_nop 0
	global_load_lds_dwordx4 v[128:129], off
	v_lshl_add_u64 v[128:129], s[62:63], 0, v[158:159]
	s_add_i32 m0, s61, 0x2000
	s_nop 0
	global_load_lds_dwordx4 v[128:129], off
	s_waitcnt vmcnt(6)
	s_barrier
	s_setprio 1
	v_mfma_f32_16x16x32_bf16 v[52:55], v[200:203], v[144:147], v[52:55]
	v_mfma_f32_16x16x32_bf16 v[48:51], v[210:213], v[144:147], v[48:51]
	v_mfma_f32_16x16x32_bf16 v[36:39], v[200:203], v[168:171], v[36:39]
	v_mfma_f32_16x16x32_bf16 v[32:35], v[210:213], v[168:171], v[32:35]
	v_mfma_f32_16x16x32_bf16 v[20:23], v[200:203], v[176:179], v[20:23]
	v_mfma_f32_16x16x32_bf16 v[16:19], v[210:213], v[176:179], v[16:19]
	v_mfma_f32_16x16x32_bf16 v[4:7], v[200:203], v[192:195], v[4:7]
	v_mfma_f32_16x16x32_bf16 v[0:3], v[210:213], v[192:195], v[0:3]
	v_mfma_f32_16x16x32_bf16 v[52:55], v[206:209], v[148:151], v[52:55]
	v_mfma_f32_16x16x32_bf16 v[48:51], v[214:217], v[148:151], v[48:51]
	v_mfma_f32_16x16x32_bf16 v[36:39], v[206:209], v[172:175], v[36:39]
	v_mfma_f32_16x16x32_bf16 v[32:35], v[214:217], v[172:175], v[32:35]
	v_mfma_f32_16x16x32_bf16 v[20:23], v[206:209], v[180:183], v[20:23]
	v_mfma_f32_16x16x32_bf16 v[16:19], v[214:217], v[180:183], v[16:19]
	v_mfma_f32_16x16x32_bf16 v[4:7], v[206:209], v[196:199], v[4:7]
	v_mfma_f32_16x16x32_bf16 v[0:3], v[214:217], v[196:199], v[0:3]
	s_setprio 0
	s_add_i32 s61, 0, 0x18000
	v_add_u32_e32 v140, s61, v187
	s_barrier
	ds_read_b128 v[128:131], v140
	ds_read_b128 v[132:135], v140 offset:1024
	ds_read_b128 v[136:139], v140 offset:2048
	ds_read_b128 v[140:143], v140 offset:3072
	s_add_u32 s54, s54, 0x100000
	s_addc_u32 s55, s55, 0
	s_mov_b32 m0, s39
	v_lshl_add_u64 v[200:201], s[54:55], 0, v[152:153]
	ds_read_b128 v[144:147], v190 offset:32768
	ds_read_b128 v[148:151], v190 offset:33792
	ds_read_b128 v[168:171], v190 offset:34816
	ds_read_b128 v[172:175], v190 offset:35840
	ds_read_b128 v[176:179], v190 offset:36864
	ds_read_b128 v[180:183], v190 offset:37888
	ds_read_b128 v[192:195], v190 offset:38912
	ds_read_b128 v[196:199], v190 offset:39936
	global_load_lds_dwordx4 v[200:201], off
	v_lshl_add_u64 v[200:201], s[54:55], 0, v[156:157]
	s_mov_b32 m0, s42
	s_nop 0
	global_load_lds_dwordx4 v[200:201], off
	s_waitcnt lgkmcnt(8)
	s_barrier
	s_waitcnt lgkmcnt(0)
	s_setprio 1
	s_waitcnt lgkmcnt(0)
	v_mfma_f32_16x16x32_bf16 v[124:127], v[128:131], v[144:147], v[124:127]
	v_mfma_f32_16x16x32_bf16 v[120:123], v[136:139], v[144:147], v[120:123]
	v_mfma_f32_16x16x32_bf16 v[108:111], v[128:131], v[168:171], v[108:111]
	v_mfma_f32_16x16x32_bf16 v[104:107], v[136:139], v[168:171], v[104:107]
	v_mfma_f32_16x16x32_bf16 v[92:95], v[128:131], v[176:179], v[92:95]
	v_mfma_f32_16x16x32_bf16 v[88:91], v[136:139], v[176:179], v[88:91]
	v_mfma_f32_16x16x32_bf16 v[76:79], v[128:131], v[192:195], v[76:79]
	v_mfma_f32_16x16x32_bf16 v[72:75], v[136:139], v[192:195], v[72:75]
	v_mfma_f32_16x16x32_bf16 v[124:127], v[132:135], v[148:151], v[124:127]
	v_mfma_f32_16x16x32_bf16 v[120:123], v[140:143], v[148:151], v[120:123]
	v_mfma_f32_16x16x32_bf16 v[108:111], v[132:135], v[172:175], v[108:111]
	v_mfma_f32_16x16x32_bf16 v[104:107], v[140:143], v[172:175], v[104:107]
	v_mfma_f32_16x16x32_bf16 v[92:95], v[132:135], v[180:183], v[92:95]
	v_mfma_f32_16x16x32_bf16 v[88:91], v[140:143], v[180:183], v[88:91]
	v_mfma_f32_16x16x32_bf16 v[76:79], v[132:135], v[196:199], v[76:79]
	v_mfma_f32_16x16x32_bf16 v[72:75], v[140:143], v[196:199], v[72:75]
	s_setprio 0
	s_barrier
	s_add_i32 s54, 0, 0x1c000
	s_add_i32 s55, s61, s33
	v_add_u32_e32 v214, s54, v187
	v_lshl_add_u64 v[184:185], v[184:185], 0, s[18:19]
	s_mov_b32 m0, s55
	ds_read_b128 v[200:203], v214
	ds_read_b128 v[206:209], v214 offset:1024
	ds_read_b128 v[210:213], v214 offset:2048
	ds_read_b128 v[214:217], v214 offset:3072
	global_load_lds_dwordx4 v[184:185], off
	v_lshl_add_u64 v[184:185], v[218:219], 0, s[18:19]
	s_add_i32 m0, s55, 0x2000
	s_nop 0
	global_load_lds_dwordx4 v[184:185], off
	s_barrier
	s_waitcnt lgkmcnt(0)
	s_setprio 1
	s_waitcnt lgkmcnt(0)
	v_mfma_f32_16x16x32_bf16 v[116:119], v[200:203], v[144:147], v[116:119]
	v_mfma_f32_16x16x32_bf16 v[112:115], v[210:213], v[144:147], v[112:115]
	v_mfma_f32_16x16x32_bf16 v[100:103], v[200:203], v[168:171], v[100:103]
	v_mfma_f32_16x16x32_bf16 v[96:99], v[210:213], v[168:171], v[96:99]
	v_mfma_f32_16x16x32_bf16 v[84:87], v[200:203], v[176:179], v[84:87]
	v_mfma_f32_16x16x32_bf16 v[80:83], v[210:213], v[176:179], v[80:83]
	v_mfma_f32_16x16x32_bf16 v[68:71], v[200:203], v[192:195], v[68:71]
	v_mfma_f32_16x16x32_bf16 v[64:67], v[210:213], v[192:195], v[64:67]
	v_mfma_f32_16x16x32_bf16 v[116:119], v[206:209], v[148:151], v[116:119]
	v_mfma_f32_16x16x32_bf16 v[112:115], v[214:217], v[148:151], v[112:115]
	v_mfma_f32_16x16x32_bf16 v[100:103], v[206:209], v[172:175], v[100:103]
	v_mfma_f32_16x16x32_bf16 v[96:99], v[214:217], v[172:175], v[96:99]
	v_mfma_f32_16x16x32_bf16 v[84:87], v[206:209], v[180:183], v[84:87]
	v_mfma_f32_16x16x32_bf16 v[80:83], v[214:217], v[180:183], v[80:83]
	v_mfma_f32_16x16x32_bf16 v[68:71], v[206:209], v[196:199], v[68:71]
	v_mfma_f32_16x16x32_bf16 v[64:67], v[214:217], v[196:199], v[64:67]
	s_setprio 0
	s_mov_b32 m0, s44
	v_lshl_add_u64 v[184:185], v[220:221], 0, s[18:19]
	s_barrier
	ds_read_b128 v[144:147], v190 offset:49152
	ds_read_b128 v[148:151], v190 offset:50176
	ds_read_b128 v[168:171], v190 offset:51200
	ds_read_b128 v[172:175], v190 offset:52224
	ds_read_b128 v[176:179], v190 offset:53248
	ds_read_b128 v[180:183], v190 offset:54272
	ds_read_b128 v[192:195], v190 offset:55296
	ds_read_b128 v[196:199], v190 offset:56320
	global_load_lds_dwordx4 v[184:185], off
	v_lshl_add_u64 v[184:185], v[222:223], 0, s[18:19]
	s_mov_b32 m0, s45
	s_nop 0
	global_load_lds_dwordx4 v[184:185], off
	s_barrier
	s_waitcnt lgkmcnt(0)
	s_setprio 1
	s_waitcnt lgkmcnt(0)
	v_mfma_f32_16x16x32_bf16 v[60:63], v[128:131], v[144:147], v[60:63]
	v_mfma_f32_16x16x32_bf16 v[56:59], v[136:139], v[144:147], v[56:59]
	v_mfma_f32_16x16x32_bf16 v[44:47], v[128:131], v[168:171], v[44:47]
	v_mfma_f32_16x16x32_bf16 v[40:43], v[136:139], v[168:171], v[40:43]
	v_mfma_f32_16x16x32_bf16 v[28:31], v[128:131], v[176:179], v[28:31]
	v_mfma_f32_16x16x32_bf16 v[24:27], v[136:139], v[176:179], v[24:27]
	v_mfma_f32_16x16x32_bf16 v[12:15], v[128:131], v[192:195], v[12:15]
	v_mfma_f32_16x16x32_bf16 v[8:11], v[136:139], v[192:195], v[8:11]
	v_mfma_f32_16x16x32_bf16 v[60:63], v[132:135], v[148:151], v[60:63]
	v_mfma_f32_16x16x32_bf16 v[56:59], v[140:143], v[148:151], v[56:59]
	v_mfma_f32_16x16x32_bf16 v[44:47], v[132:135], v[172:175], v[44:47]
	v_mfma_f32_16x16x32_bf16 v[40:43], v[140:143], v[172:175], v[40:43]
	v_mfma_f32_16x16x32_bf16 v[28:31], v[132:135], v[180:183], v[28:31]
	v_mfma_f32_16x16x32_bf16 v[24:27], v[140:143], v[180:183], v[24:27]
	v_mfma_f32_16x16x32_bf16 v[12:15], v[132:135], v[196:199], v[12:15]
	v_mfma_f32_16x16x32_bf16 v[8:11], v[140:143], v[196:199], v[8:11]
	s_setprio 0
	s_barrier
	s_add_u32 s52, s52, 0x100080
	s_addc_u32 s53, s53, 0
	s_add_i32 s54, s54, s33
	v_lshl_add_u64 v[128:129], s[52:53], 0, v[154:155]
	s_mov_b32 m0, s54
	s_nop 0
	global_load_lds_dwordx4 v[128:129], off
	v_lshl_add_u64 v[128:129], s[52:53], 0, v[158:159]
	s_add_i32 m0, s54, 0x2000
	s_nop 0
	global_load_lds_dwordx4 v[128:129], off
	s_waitcnt vmcnt(6)
	s_cmp_eq_u32 s60, 58
	s_cbranch_scc0 .Ler_1062_skip
	s_lshl_b32 s84, s36, 19
	s_lshl_b32 s85, s38, 9
	s_add_u32 s84, s84, s85
	s_add_u32 s84, s14, s84
	s_addc_u32 s85, s15, 0
	v_lshlrev_b32_e32 v236, 11, v186
	v_lshl_add_u32 v236, v188, 1, v236
	global_load_dwordx4 v[224:227], v236, s[84:85]
	global_load_dwordx4 v[228:231], v236, s[84:85] offset:256
	s_add_u32 s86, s84, 0x8000
	s_addc_u32 s87, s85, 0
	global_load_dwordx4 v[232:235], v236, s[86:87]
	global_load_dwordx4 v[240:243], v236, s[86:87] offset:256
	s_add_u32 s86, s84, 0x10000
	s_addc_u32 s87, s85, 0
	global_load_dwordx4 v[244:247], v236, s[86:87]
	global_load_dwordx4 v[248:251], v236, s[86:87] offset:256
	s_add_u32 s86, s84, 0x18000
	s_addc_u32 s87, s85, 0
	global_load_dwordx4 v[252:255], v236, s[86:87]
.Ler_1062_skip:
	s_barrier
	s_setprio 1
	v_mfma_f32_16x16x32_bf16 v[52:55], v[200:203], v[144:147], v[52:55]
	v_mfma_f32_16x16x32_bf16 v[48:51], v[210:213], v[144:147], v[48:51]
	v_mfma_f32_16x16x32_bf16 v[36:39], v[200:203], v[168:171], v[36:39]
	v_mfma_f32_16x16x32_bf16 v[32:35], v[210:213], v[168:171], v[32:35]
	v_mfma_f32_16x16x32_bf16 v[20:23], v[200:203], v[176:179], v[20:23]
	v_mfma_f32_16x16x32_bf16 v[16:19], v[210:213], v[176:179], v[16:19]
	v_mfma_f32_16x16x32_bf16 v[4:7], v[200:203], v[192:195], v[4:7]
	v_mfma_f32_16x16x32_bf16 v[0:3], v[210:213], v[192:195], v[0:3]
	v_mfma_f32_16x16x32_bf16 v[52:55], v[206:209], v[148:151], v[52:55]
	v_mfma_f32_16x16x32_bf16 v[48:51], v[214:217], v[148:151], v[48:51]
	v_mfma_f32_16x16x32_bf16 v[36:39], v[206:209], v[172:175], v[36:39]
	v_mfma_f32_16x16x32_bf16 v[32:35], v[214:217], v[172:175], v[32:35]
	v_mfma_f32_16x16x32_bf16 v[20:23], v[206:209], v[180:183], v[20:23]
	v_mfma_f32_16x16x32_bf16 v[16:19], v[214:217], v[180:183], v[16:19]
	v_mfma_f32_16x16x32_bf16 v[4:7], v[206:209], v[196:199], v[4:7]
	v_mfma_f32_16x16x32_bf16 v[0:3], v[214:217], v[196:199], v[0:3]
	s_setprio 0
	s_add_i32 s60, s60, 2
	s_add_u32 s50, s50, 0x100
	s_addc_u32 s51, s51, 0
	s_add_u32 s58, s58, 0x100
	s_addc_u32 s59, s59, 0
	s_cmp_gt_u32 s60, 61
	s_barrier
	s_cbranch_scc0 .LBB0_1062
	v_lshl_or_b32 v168, s38, 8, v188
	v_lshl_add_u32 v170, s36, 8, v186
	v_ashrrev_i32_e32 v169, 31, v168
	v_lshlrev_b64 v[202:203], 1, v[168:169]
	v_ashrrev_i32_e32 v171, 31, v170
	v_or_b32_e32 v182, 16, v170
	v_lshl_add_u64 v[172:173], s[14:15], 0, v[202:203]
	v_lshlrev_b64 v[206:207], 11, v[170:171]
	v_ashrrev_i32_e32 v183, 31, v182
	v_or_b32_e32 v178, 32, v170
	v_lshl_add_u64 v[128:129], v[172:173], 0, v[206:207]
	v_lshlrev_b64 v[184:185], 11, v[182:183]
	v_ashrrev_i32_e32 v179, 31, v178
	v_or_b32_e32 v174, 48, v170
	v_mov_b32_e32 v194, v224
	v_mov_b32_e32 v195, v225
	v_mov_b32_e32 v196, v226
	v_mov_b32_e32 v197, v227
	v_mov_b32_e32 v198, v228
	v_mov_b32_e32 v199, v229
	v_mov_b32_e32 v200, v230
	v_mov_b32_e32 v201, v231
	v_lshl_add_u64 v[128:129], v[172:173], 0, v[184:185]
	v_lshlrev_b64 v[180:181], 11, v[178:179]
	v_ashrrev_i32_e32 v175, 31, v174
	v_mov_b32_e32 v148, v232
	v_mov_b32_e32 v149, v233
	v_mov_b32_e32 v150, v234
	v_mov_b32_e32 v151, v235
	v_mov_b32_e32 v144, v240
	v_mov_b32_e32 v145, v241
	v_mov_b32_e32 v146, v242
	v_mov_b32_e32 v147, v243
	v_lshl_add_u64 v[128:129], v[172:173], 0, v[180:181]
	v_lshlrev_b64 v[176:177], 11, v[174:175]
	v_mov_b32_e32 v140, v244
	v_mov_b32_e32 v141, v245
	v_mov_b32_e32 v142, v246
	v_mov_b32_e32 v143, v247
	v_mov_b32_e32 v136, v248
	v_mov_b32_e32 v137, v249
	v_mov_b32_e32 v138, v250
	v_mov_b32_e32 v139, v251
	v_lshl_add_u64 v[128:129], v[172:173], 0, v[176:177]
	v_mov_b32_e32 v132, v252
	v_mov_b32_e32 v133, v253
	v_mov_b32_e32 v134, v254
	v_mov_b32_e32 v135, v255
	s_nop 0
	global_load_dwordx4 v[128:131], v[128:129], off offset:256
	v_and_b32_e32 v193, 64, v205
	v_xor_b32_e32 v192, 16, v205
	v_add_u32_e32 v208, 64, v193
	v_cmp_lt_i32_e32 vcc, v192, v208
	s_nop 1
	v_cndmask_b32_e32 v192, v205, v192, vcc
	v_lshlrev_b32_e32 v193, 2, v192
	v_xor_b32_e32 v192, 32, v205
	v_cmp_lt_i32_e32 vcc, v192, v208
	s_nop 1
	v_cndmask_b32_e32 v192, v205, v192, vcc
	v_lshlrev_b32_e32 v192, 2, v192
	v_add_u32_e32 v236, 0x80, v170
	v_ashrrev_i32_e32 v237, 31, v236
	v_lshlrev_b64 v[236:237], 11, v[236:237]
	v_lshl_add_u64 v[236:237], v[172:173], 0, v[236:237]
	global_load_dwordx4 v[224:227], v[236:237], off
	global_load_dwordx4 v[228:231], v[236:237], off offset:256
	v_add_u32_e32 v236, 0x90, v170
	v_ashrrev_i32_e32 v237, 31, v236
	v_lshlrev_b64 v[236:237], 11, v[236:237]
	v_lshl_add_u64 v[236:237], v[172:173], 0, v[236:237]
	global_load_dwordx4 v[232:235], v[236:237], off
	global_load_dwordx4 v[240:243], v[236:237], off offset:256
	v_add_u32_e32 v236, 0xa0, v170
	v_ashrrev_i32_e32 v237, 31, v236
	v_lshlrev_b64 v[236:237], 11, v[236:237]
	v_lshl_add_u64 v[236:237], v[172:173], 0, v[236:237]
	global_load_dwordx4 v[244:247], v[236:237], off
	global_load_dwordx4 v[248:251], v[236:237], off offset:256
	v_add_u32_e32 v236, 0xb0, v170
	v_ashrrev_i32_e32 v237, 31, v236
	v_lshlrev_b64 v[236:237], 11, v[236:237]
	v_lshl_add_u64 v[236:237], v[172:173], 0, v[236:237]
	global_load_dwordx4 v[252:255], v[236:237], off
	s_waitcnt vmcnt(24)
	v_lshlrev_b32_e32 v208, 16, v194
	v_and_b32_e32 v209, 0xffff0000, v194
	v_lshlrev_b32_e32 v194, 16, v195
	v_and_b32_e32 v195, 0xffff0000, v195
	v_lshlrev_b32_e32 v210, 16, v196
	v_and_b32_e32 v211, 0xffff0000, v196
	v_lshlrev_b32_e32 v196, 16, v197
	v_and_b32_e32 v197, 0xffff0000, v197
	v_pk_add_f32 v[126:127], v[126:127], v[194:195]
	v_pk_add_f32 v[194:195], v[122:123], v[196:197]
	v_pk_add_f32 v[196:197], v[120:121], v[210:211]
	v_pk_add_f32 v[124:125], v[124:125], v[208:209]
	v_cvt_pk_bf16_f32 v122, v196, v197
	v_mul_f32_e32 v196, v196, v196
	v_cvt_pk_bf16_f32 v120, v124, v125
	v_fmac_f32_e32 v196, v124, v124
	v_mul_f32_e32 v124, v197, v197
	v_fmac_f32_e32 v124, v125, v125
	v_mul_f32_e32 v125, v194, v194
	v_add_f32_e32 v124, v196, v124
	v_fmac_f32_e32 v125, v126, v126
	v_add_f32_e32 v124, v125, v124
	v_mul_f32_e32 v125, v195, v195
	v_cvt_pk_bf16_f32 v121, v126, v127
	v_cvt_pk_bf16_f32 v123, v194, v195
	v_fmac_f32_e32 v125, v127, v127
	v_lshlrev_b32_e32 v126, 16, v199
	v_and_b32_e32 v127, 0xffff0000, v199
	v_lshlrev_b32_e32 v194, 16, v200
	v_and_b32_e32 v195, 0xffff0000, v200
	v_add_f32_e32 v208, v125, v124
	v_lshlrev_b32_e32 v124, 16, v198
	v_and_b32_e32 v125, 0xffff0000, v198
	v_pk_add_f32 v[118:119], v[118:119], v[126:127]
	v_pk_add_f32 v[126:127], v[112:113], v[194:195]
	v_pk_add_f32 v[116:117], v[116:117], v[124:125]
	v_mul_f32_e32 v112, v126, v126
	v_lshlrev_b32_e32 v196, 16, v201
	v_and_b32_e32 v197, 0xffff0000, v201
	v_fmac_f32_e32 v112, v116, v116
	v_mul_f32_e32 v113, v127, v127
	v_pk_add_f32 v[124:125], v[114:115], v[196:197]
	v_add_f32_e32 v112, v112, v208
	v_fmac_f32_e32 v113, v117, v117
	v_add_f32_e32 v112, v113, v112
	v_mul_f32_e32 v113, v124, v124
	v_fmac_f32_e32 v113, v118, v118
	v_add_f32_e32 v112, v113, v112
	v_mul_f32_e32 v113, v125, v125
	v_fmac_f32_e32 v113, v119, v119
	v_add_f32_e32 v115, v113, v112
	ds_bpermute_b32 v196, v193, v115
	v_lshl_add_u64 v[112:113], s[14:15], 0, v[206:207]
	v_lshl_add_u64 v[194:195], v[112:113], 0, v[202:203]
	v_cvt_pk_bf16_f32 v114, v116, v117
	v_cvt_pk_bf16_f32 v116, v126, v127
	s_waitcnt lgkmcnt(0)
	v_add_f32_e32 v112, v115, v196
	ds_bpermute_b32 v113, v192, v112
	v_cvt_pk_bf16_f32 v115, v118, v119
	v_cvt_pk_bf16_f32 v117, v124, v125
	global_store_dwordx4 v[194:195], v[120:123], off
	global_store_dwordx4 v[194:195], v[114:117], off offset:256
	s_and_saveexec_b64 s[36:37], s[8:9]
	s_cbranch_execz .LBB0_1065
	s_waitcnt lgkmcnt(0)
	v_add_f32_e32 v112, v112, v113
	v_mul_f32_e32 v112, 0x4b800000, v112
	v_trunc_f32_e32 v112, v112
	v_mul_f32_e32 v113, 0x2f800000, v112
	v_floor_f32_e32 v113, v113
	v_fmac_f32_e32 v112, 0xcf800000, v113
	v_cvt_u32_f32_e32 v112, v112
	v_cvt_u32_f32_e32 v113, v113
	v_lshl_add_u64 v[114:115], v[170:171], 3, s[16:17]
	global_atomic_add_x2 v[114:115], v[112:113], off

.LBB0_1069:
	s_or_b64 exec, exec, s[36:37]
	v_lshlrev_b32_e32 v82, 16, v133
	v_and_b32_e32 v83, 0xffff0000, v133
	v_lshlrev_b32_e32 v84, 16, v134
	v_and_b32_e32 v85, 0xffff0000, v134
	v_lshlrev_b32_e32 v80, 16, v132
	s_waitcnt lgkmcnt(0)
	v_and_b32_e32 v81, 0xffff0000, v132
	v_lshlrev_b32_e32 v86, 16, v135
	v_and_b32_e32 v87, 0xffff0000, v135
	v_pk_add_f32 v[78:79], v[78:79], v[82:83]
	v_pk_add_f32 v[82:83], v[72:73], v[84:85]
	v_pk_add_f32 v[76:77], v[76:77], v[80:81]
	v_pk_add_f32 v[80:81], v[74:75], v[86:87]
	v_cvt_pk_bf16_f32 v74, v82, v83
	v_mul_f32_e32 v82, v82, v82
	v_cvt_pk_bf16_f32 v72, v76, v77
	v_fmac_f32_e32 v82, v76, v76
	v_mul_f32_e32 v76, v83, v83
	v_fmac_f32_e32 v76, v77, v77
	v_mul_f32_e32 v77, v80, v80
	v_add_f32_e32 v76, v82, v76
	v_fmac_f32_e32 v77, v78, v78
	v_add_f32_e32 v76, v77, v76
	v_mul_f32_e32 v77, v81, v81
	v_cvt_pk_bf16_f32 v73, v78, v79
	v_cvt_pk_bf16_f32 v75, v80, v81
	v_fmac_f32_e32 v77, v79, v79
	s_waitcnt vmcnt(13)
	v_lshlrev_b32_e32 v78, 16, v129
	v_and_b32_e32 v79, 0xffff0000, v129
	v_lshlrev_b32_e32 v80, 16, v130
	v_and_b32_e32 v81, 0xffff0000, v130
	v_add_f32_e32 v84, v77, v76
	v_lshlrev_b32_e32 v76, 16, v128
	v_and_b32_e32 v77, 0xffff0000, v128
	v_pk_add_f32 v[70:71], v[70:71], v[78:79]
	v_pk_add_f32 v[78:79], v[64:65], v[80:81]
	v_pk_add_f32 v[68:69], v[68:69], v[76:77]
	v_mul_f32_e32 v64, v78, v78
	v_lshlrev_b32_e32 v82, 16, v131
	v_and_b32_e32 v83, 0xffff0000, v131
	v_fmac_f32_e32 v64, v68, v68
	v_mul_f32_e32 v65, v79, v79
	v_pk_add_f32 v[76:77], v[66:67], v[82:83]
	v_add_f32_e32 v64, v64, v84
	v_fmac_f32_e32 v65, v69, v69
	v_add_f32_e32 v64, v65, v64
	v_mul_f32_e32 v65, v76, v76
	v_fmac_f32_e32 v65, v70, v70
	v_add_f32_e32 v64, v65, v64
	v_mul_f32_e32 v65, v77, v77
	v_fmac_f32_e32 v65, v71, v71
	v_add_f32_e32 v67, v65, v64
	ds_bpermute_b32 v82, v193, v67
	v_lshl_add_u64 v[64:65], s[14:15], 0, v[176:177]
	v_lshl_add_u64 v[80:81], v[168:169], 1, v[64:65]
	v_cvt_pk_bf16_f32 v66, v68, v69
	v_cvt_pk_bf16_f32 v68, v78, v79
	s_waitcnt lgkmcnt(0)
	v_add_f32_e32 v64, v67, v82
	ds_bpermute_b32 v65, v192, v64
	v_cvt_pk_bf16_f32 v67, v70, v71
	v_cvt_pk_bf16_f32 v69, v76, v77
	global_store_dwordx4 v[80:81], v[72:75], off
	global_store_dwordx4 v[80:81], v[66:69], off offset:256
	s_and_saveexec_b64 s[36:37], s[8:9]
	s_cbranch_execz .LBB0_1071
	s_waitcnt lgkmcnt(0)
	v_add_f32_e32 v64, v64, v65
	v_mul_f32_e32 v64, 0x4b800000, v64
	v_trunc_f32_e32 v64, v64
	v_mul_f32_e32 v65, 0x2f800000, v64
	v_floor_f32_e32 v65, v65
	v_fmac_f32_e32 v64, 0xcf800000, v65
	v_cvt_u32_f32_e32 v64, v64
	v_cvt_u32_f32_e32 v65, v65
	v_lshl_add_u64 v[66:67], v[174:175], 3, s[16:17]
	global_atomic_add_x2 v[66:67], v[64:65], off

.LBB0_1894:
	ds_read_b128 v[128:131], v189
	ds_read_b128 v[132:135], v189 offset:1024
	ds_read_b128 v[136:139], v189 offset:2048
	ds_read_b128 v[140:143], v189 offset:3072
	s_add_u32 s42, s40, 0xfffc0080
	s_addc_u32 s43, s41, -1
	s_cmp_eq_u32 s57, 12
	s_cselect_b32 s45, s29, s43
	s_cselect_b32 s44, s37, s42
	s_cselect_b32 s43, s27, s56
	s_cselect_b32 s42, s54, s55
	v_lshl_add_u64 v[184:185], s[40:41], 0, v[160:161]
	s_add_i32 m0, s20, 0xc000
	ds_read_b128 v[144:147], v190
	ds_read_b128 v[148:151], v190 offset:1024
	ds_read_b128 v[168:171], v190 offset:2048
	ds_read_b128 v[172:175], v190 offset:3072
	ds_read_b128 v[176:179], v190 offset:4096
	ds_read_b128 v[180:183], v190 offset:5120
	ds_read_b128 v[192:195], v190 offset:6144
	ds_read_b128 v[196:199], v190 offset:7168
	global_load_lds_dwordx4 v[184:185], off
	v_lshl_add_u64 v[184:185], s[40:41], 0, v[162:163]
	s_add_i32 m0, s20, 0xe000
	s_nop 0
	global_load_lds_dwordx4 v[184:185], off
	s_waitcnt lgkmcnt(8)
	s_barrier
	s_waitcnt lgkmcnt(0)
	s_setprio 1
	s_waitcnt lgkmcnt(0)
	v_mfma_f32_16x16x32_bf16 v[124:127], v[128:131], v[144:147], v[124:127]
	v_mfma_f32_16x16x32_bf16 v[120:123], v[136:139], v[144:147], v[120:123]
	v_mfma_f32_16x16x32_bf16 v[108:111], v[128:131], v[168:171], v[108:111]
	v_mfma_f32_16x16x32_bf16 v[104:107], v[136:139], v[168:171], v[104:107]
	v_mfma_f32_16x16x32_bf16 v[92:95], v[128:131], v[176:179], v[92:95]
	v_mfma_f32_16x16x32_bf16 v[88:91], v[136:139], v[176:179], v[88:91]
	v_mfma_f32_16x16x32_bf16 v[76:79], v[128:131], v[192:195], v[76:79]
	v_mfma_f32_16x16x32_bf16 v[72:75], v[136:139], v[192:195], v[72:75]
	v_mfma_f32_16x16x32_bf16 v[124:127], v[132:135], v[148:151], v[124:127]
	v_mfma_f32_16x16x32_bf16 v[120:123], v[140:143], v[148:151], v[120:123]
	v_mfma_f32_16x16x32_bf16 v[108:111], v[132:135], v[172:175], v[108:111]
	v_mfma_f32_16x16x32_bf16 v[104:107], v[140:143], v[172:175], v[104:107]
	v_mfma_f32_16x16x32_bf16 v[92:95], v[132:135], v[180:183], v[92:95]
	v_mfma_f32_16x16x32_bf16 v[88:91], v[140:143], v[180:183], v[88:91]
	v_mfma_f32_16x16x32_bf16 v[76:79], v[132:135], v[196:199], v[76:79]
	v_mfma_f32_16x16x32_bf16 v[72:75], v[140:143], v[196:199], v[72:75]
	s_setprio 0
	s_barrier
	s_add_i32 s58, s52, s3
	v_lshl_add_u64 v[184:185], s[42:43], 0, v[154:155]
	s_mov_b32 m0, s58
	ds_read_b128 v[200:203], v191
	ds_read_b128 v[206:209], v191 offset:1024
	ds_read_b128 v[210:213], v191 offset:2048
	ds_read_b128 v[214:217], v191 offset:3072
	global_load_lds_dwordx4 v[184:185], off
	v_lshl_add_u64 v[218:219], s[42:43], 0, v[158:159]
	s_add_i32 m0, s58, 0x2000
	s_nop 0
	global_load_lds_dwordx4 v[218:219], off
	s_barrier
	s_waitcnt lgkmcnt(0)
	s_setprio 1
	s_waitcnt lgkmcnt(0)
	v_mfma_f32_16x16x32_bf16 v[116:119], v[200:203], v[144:147], v[116:119]
	v_mfma_f32_16x16x32_bf16 v[112:115], v[210:213], v[144:147], v[112:115]
	v_mfma_f32_16x16x32_bf16 v[100:103], v[200:203], v[168:171], v[100:103]
	v_mfma_f32_16x16x32_bf16 v[96:99], v[210:213], v[168:171], v[96:99]
	v_mfma_f32_16x16x32_bf16 v[84:87], v[200:203], v[176:179], v[84:87]
	v_mfma_f32_16x16x32_bf16 v[80:83], v[210:213], v[176:179], v[80:83]
	v_mfma_f32_16x16x32_bf16 v[68:71], v[200:203], v[192:195], v[68:71]
	v_mfma_f32_16x16x32_bf16 v[64:67], v[210:213], v[192:195], v[64:67]
	v_mfma_f32_16x16x32_bf16 v[116:119], v[206:209], v[148:151], v[116:119]
	v_mfma_f32_16x16x32_bf16 v[112:115], v[214:217], v[148:151], v[112:115]
	v_mfma_f32_16x16x32_bf16 v[100:103], v[206:209], v[172:175], v[100:103]
	v_mfma_f32_16x16x32_bf16 v[96:99], v[214:217], v[172:175], v[96:99]
	v_mfma_f32_16x16x32_bf16 v[84:87], v[206:209], v[180:183], v[84:87]
	v_mfma_f32_16x16x32_bf16 v[80:83], v[214:217], v[180:183], v[80:83]
	v_mfma_f32_16x16x32_bf16 v[68:71], v[206:209], v[196:199], v[68:71]
	v_mfma_f32_16x16x32_bf16 v[64:67], v[214:217], v[196:199], v[64:67]
	s_setprio 0
	s_mov_b32 m0, s20
	v_lshl_add_u64 v[220:221], s[44:45], 0, v[152:153]
	s_barrier
	ds_read_b128 v[144:147], v190 offset:16384
	ds_read_b128 v[148:151], v190 offset:17408
	ds_read_b128 v[168:171], v190 offset:18432
	ds_read_b128 v[172:175], v190 offset:19456
	ds_read_b128 v[176:179], v190 offset:20480
	ds_read_b128 v[180:183], v190 offset:21504
	ds_read_b128 v[192:195], v190 offset:22528
	ds_read_b128 v[196:199], v190 offset:23552
	global_load_lds_dwordx4 v[220:221], off
	v_lshl_add_u64 v[222:223], s[44:45], 0, v[156:157]
	s_mov_b32 m0, s21
	s_nop 0
	global_load_lds_dwordx4 v[222:223], off
	s_barrier
	s_waitcnt lgkmcnt(0)
	s_setprio 1
	s_waitcnt lgkmcnt(0)
	v_mfma_f32_16x16x32_bf16 v[60:63], v[128:131], v[144:147], v[60:63]
	v_mfma_f32_16x16x32_bf16 v[56:59], v[136:139], v[144:147], v[56:59]
	v_mfma_f32_16x16x32_bf16 v[44:47], v[128:131], v[168:171], v[44:47]
	v_mfma_f32_16x16x32_bf16 v[40:43], v[136:139], v[168:171], v[40:43]
	v_mfma_f32_16x16x32_bf16 v[28:31], v[128:131], v[176:179], v[28:31]
	v_mfma_f32_16x16x32_bf16 v[24:27], v[136:139], v[176:179], v[24:27]
	v_mfma_f32_16x16x32_bf16 v[12:15], v[128:131], v[192:195], v[12:15]
	v_mfma_f32_16x16x32_bf16 v[8:11], v[136:139], v[192:195], v[8:11]
	v_mfma_f32_16x16x32_bf16 v[60:63], v[132:135], v[148:151], v[60:63]
	v_mfma_f32_16x16x32_bf16 v[56:59], v[140:143], v[148:151], v[56:59]
	v_mfma_f32_16x16x32_bf16 v[44:47], v[132:135], v[172:175], v[44:47]
	v_mfma_f32_16x16x32_bf16 v[40:43], v[140:143], v[172:175], v[40:43]
	v_mfma_f32_16x16x32_bf16 v[28:31], v[132:135], v[180:183], v[28:31]
	v_mfma_f32_16x16x32_bf16 v[24:27], v[140:143], v[180:183], v[24:27]
	v_mfma_f32_16x16x32_bf16 v[12:15], v[132:135], v[196:199], v[12:15]
	v_mfma_f32_16x16x32_bf16 v[8:11], v[140:143], v[196:199], v[8:11]
	s_setprio 0
	s_barrier
	s_add_u32 s58, s42, 0x40000
	s_addc_u32 s59, s43, 0
	s_add_i32 s60, s53, s3
	v_lshl_add_u64 v[128:129], s[58:59], 0, v[154:155]
	s_mov_b32 m0, s60
	s_nop 0
	global_load_lds_dwordx4 v[128:129], off
	v_lshl_add_u64 v[128:129], s[58:59], 0, v[158:159]
	s_add_i32 m0, s60, 0x2000
	s_nop 0
	global_load_lds_dwordx4 v[128:129], off
	s_waitcnt vmcnt(6)
	s_barrier
	s_setprio 1
	v_mfma_f32_16x16x32_bf16 v[52:55], v[200:203], v[144:147], v[52:55]
	v_mfma_f32_16x16x32_bf16 v[48:51], v[210:213], v[144:147], v[48:51]
	v_mfma_f32_16x16x32_bf16 v[36:39], v[200:203], v[168:171], v[36:39]
	v_mfma_f32_16x16x32_bf16 v[32:35], v[210:213], v[168:171], v[32:35]
	v_mfma_f32_16x16x32_bf16 v[20:23], v[200:203], v[176:179], v[20:23]
	v_mfma_f32_16x16x32_bf16 v[16:19], v[210:213], v[176:179], v[16:19]
	v_mfma_f32_16x16x32_bf16 v[4:7], v[200:203], v[192:195], v[4:7]
	v_mfma_f32_16x16x32_bf16 v[0:3], v[210:213], v[192:195], v[0:3]
	v_mfma_f32_16x16x32_bf16 v[52:55], v[206:209], v[148:151], v[52:55]
	v_mfma_f32_16x16x32_bf16 v[48:51], v[214:217], v[148:151], v[48:51]
	v_mfma_f32_16x16x32_bf16 v[36:39], v[206:209], v[172:175], v[36:39]
	v_mfma_f32_16x16x32_bf16 v[32:35], v[214:217], v[172:175], v[32:35]
	v_mfma_f32_16x16x32_bf16 v[20:23], v[206:209], v[180:183], v[20:23]
	v_mfma_f32_16x16x32_bf16 v[16:19], v[214:217], v[180:183], v[16:19]
	v_mfma_f32_16x16x32_bf16 v[4:7], v[206:209], v[196:199], v[4:7]
	v_mfma_f32_16x16x32_bf16 v[0:3], v[214:217], v[196:199], v[0:3]
	s_setprio 0
	s_add_i32 s58, 0, 0x18000
	v_add_u32_e32 v140, s58, v187
	s_barrier
	ds_read_b128 v[128:131], v140
	ds_read_b128 v[132:135], v140 offset:1024
	ds_read_b128 v[136:139], v140 offset:2048
	ds_read_b128 v[140:143], v140 offset:3072
	s_add_u32 s44, s44, 0x40000
	s_addc_u32 s45, s45, 0
	s_mov_b32 m0, s33
	v_lshl_add_u64 v[200:201], s[44:45], 0, v[152:153]
	ds_read_b128 v[144:147], v190 offset:32768
	ds_read_b128 v[148:151], v190 offset:33792
	ds_read_b128 v[168:171], v190 offset:34816
	ds_read_b128 v[172:175], v190 offset:35840
	ds_read_b128 v[176:179], v190 offset:36864
	ds_read_b128 v[180:183], v190 offset:37888
	ds_read_b128 v[192:195], v190 offset:38912
	ds_read_b128 v[196:199], v190 offset:39936
	global_load_lds_dwordx4 v[200:201], off
	v_lshl_add_u64 v[200:201], s[44:45], 0, v[156:157]
	s_mov_b32 m0, s39
	s_nop 0
	global_load_lds_dwordx4 v[200:201], off
	s_waitcnt lgkmcnt(8)
	s_barrier
	s_waitcnt lgkmcnt(0)
	s_setprio 1
	s_waitcnt lgkmcnt(0)
	v_mfma_f32_16x16x32_bf16 v[124:127], v[128:131], v[144:147], v[124:127]
	v_mfma_f32_16x16x32_bf16 v[120:123], v[136:139], v[144:147], v[120:123]
	v_mfma_f32_16x16x32_bf16 v[108:111], v[128:131], v[168:171], v[108:111]
	v_mfma_f32_16x16x32_bf16 v[104:107], v[136:139], v[168:171], v[104:107]
	v_mfma_f32_16x16x32_bf16 v[92:95], v[128:131], v[176:179], v[92:95]
	v_mfma_f32_16x16x32_bf16 v[88:91], v[136:139], v[176:179], v[88:91]
	v_mfma_f32_16x16x32_bf16 v[76:79], v[128:131], v[192:195], v[76:79]
	v_mfma_f32_16x16x32_bf16 v[72:75], v[136:139], v[192:195], v[72:75]
	v_mfma_f32_16x16x32_bf16 v[124:127], v[132:135], v[148:151], v[124:127]
	v_mfma_f32_16x16x32_bf16 v[120:123], v[140:143], v[148:151], v[120:123]
	v_mfma_f32_16x16x32_bf16 v[108:111], v[132:135], v[172:175], v[108:111]
	v_mfma_f32_16x16x32_bf16 v[104:107], v[140:143], v[172:175], v[104:107]
	v_mfma_f32_16x16x32_bf16 v[92:95], v[132:135], v[180:183], v[92:95]
	v_mfma_f32_16x16x32_bf16 v[88:91], v[140:143], v[180:183], v[88:91]
	v_mfma_f32_16x16x32_bf16 v[76:79], v[132:135], v[196:199], v[76:79]
	v_mfma_f32_16x16x32_bf16 v[72:75], v[140:143], v[196:199], v[72:75]
	s_setprio 0
	s_barrier
	s_add_i32 s44, 0, 0x1c000
	s_add_i32 s45, s58, s3
	v_add_u32_e32 v214, s44, v187
	v_lshl_add_u64 v[184:185], v[184:185], 0, s[24:25]
	s_mov_b32 m0, s45
	ds_read_b128 v[200:203], v214
	ds_read_b128 v[206:209], v214 offset:1024
	ds_read_b128 v[210:213], v214 offset:2048
	ds_read_b128 v[214:217], v214 offset:3072
	global_load_lds_dwordx4 v[184:185], off
	v_lshl_add_u64 v[184:185], v[218:219], 0, s[24:25]
	s_add_i32 m0, s45, 0x2000
	s_nop 0
	global_load_lds_dwordx4 v[184:185], off
	s_barrier
	s_waitcnt lgkmcnt(0)
	s_setprio 1
	s_waitcnt lgkmcnt(0)
	v_mfma_f32_16x16x32_bf16 v[116:119], v[200:203], v[144:147], v[116:119]
	v_mfma_f32_16x16x32_bf16 v[112:115], v[210:213], v[144:147], v[112:115]
	v_mfma_f32_16x16x32_bf16 v[100:103], v[200:203], v[168:171], v[100:103]
	v_mfma_f32_16x16x32_bf16 v[96:99], v[210:213], v[168:171], v[96:99]
	v_mfma_f32_16x16x32_bf16 v[84:87], v[200:203], v[176:179], v[84:87]
	v_mfma_f32_16x16x32_bf16 v[80:83], v[210:213], v[176:179], v[80:83]
	v_mfma_f32_16x16x32_bf16 v[68:71], v[200:203], v[192:195], v[68:71]
	v_mfma_f32_16x16x32_bf16 v[64:67], v[210:213], v[192:195], v[64:67]
	v_mfma_f32_16x16x32_bf16 v[116:119], v[206:209], v[148:151], v[116:119]
	v_mfma_f32_16x16x32_bf16 v[112:115], v[214:217], v[148:151], v[112:115]
	v_mfma_f32_16x16x32_bf16 v[100:103], v[206:209], v[172:175], v[100:103]
	v_mfma_f32_16x16x32_bf16 v[96:99], v[214:217], v[172:175], v[96:99]
	v_mfma_f32_16x16x32_bf16 v[84:87], v[206:209], v[180:183], v[84:87]
	v_mfma_f32_16x16x32_bf16 v[80:83], v[214:217], v[180:183], v[80:83]
	v_mfma_f32_16x16x32_bf16 v[68:71], v[206:209], v[196:199], v[68:71]
	v_mfma_f32_16x16x32_bf16 v[64:67], v[214:217], v[196:199], v[64:67]
	s_setprio 0
	s_mov_b32 m0, s47
	v_lshl_add_u64 v[184:185], v[220:221], 0, s[24:25]
	s_barrier
	ds_read_b128 v[144:147], v190 offset:49152
	ds_read_b128 v[148:151], v190 offset:50176
	ds_read_b128 v[168:171], v190 offset:51200
	ds_read_b128 v[172:175], v190 offset:52224
	ds_read_b128 v[176:179], v190 offset:53248
	ds_read_b128 v[180:183], v190 offset:54272
	ds_read_b128 v[192:195], v190 offset:55296
	ds_read_b128 v[196:199], v190 offset:56320
	global_load_lds_dwordx4 v[184:185], off
	v_lshl_add_u64 v[184:185], v[222:223], 0, s[24:25]
	s_mov_b32 m0, s48
	s_nop 0
	global_load_lds_dwordx4 v[184:185], off
	s_barrier
	s_waitcnt lgkmcnt(0)
	s_setprio 1
	s_waitcnt lgkmcnt(0)
	v_mfma_f32_16x16x32_bf16 v[60:63], v[128:131], v[144:147], v[60:63]
	v_mfma_f32_16x16x32_bf16 v[56:59], v[136:139], v[144:147], v[56:59]
	v_mfma_f32_16x16x32_bf16 v[44:47], v[128:131], v[168:171], v[44:47]
	v_mfma_f32_16x16x32_bf16 v[40:43], v[136:139], v[168:171], v[40:43]
	v_mfma_f32_16x16x32_bf16 v[28:31], v[128:131], v[176:179], v[28:31]
	v_mfma_f32_16x16x32_bf16 v[24:27], v[136:139], v[176:179], v[24:27]
	v_mfma_f32_16x16x32_bf16 v[12:15], v[128:131], v[192:195], v[12:15]
	v_mfma_f32_16x16x32_bf16 v[8:11], v[136:139], v[192:195], v[8:11]
	v_mfma_f32_16x16x32_bf16 v[60:63], v[132:135], v[148:151], v[60:63]
	v_mfma_f32_16x16x32_bf16 v[56:59], v[140:143], v[148:151], v[56:59]
	v_mfma_f32_16x16x32_bf16 v[44:47], v[132:135], v[172:175], v[44:47]
	v_mfma_f32_16x16x32_bf16 v[40:43], v[140:143], v[172:175], v[40:43]
	v_mfma_f32_16x16x32_bf16 v[28:31], v[132:135], v[180:183], v[28:31]
	v_mfma_f32_16x16x32_bf16 v[24:27], v[140:143], v[180:183], v[24:27]
	v_mfma_f32_16x16x32_bf16 v[12:15], v[132:135], v[196:199], v[12:15]
	v_mfma_f32_16x16x32_bf16 v[8:11], v[140:143], v[196:199], v[8:11]
	s_setprio 0
	s_barrier
	s_add_u32 s42, s42, 0x40080
	s_addc_u32 s43, s43, 0
	s_add_i32 s44, s44, s3
	v_lshl_add_u64 v[128:129], s[42:43], 0, v[154:155]
	s_mov_b32 m0, s44
	s_nop 0
	global_load_lds_dwordx4 v[128:129], off
	v_lshl_add_u64 v[128:129], s[42:43], 0, v[158:159]
	s_add_i32 m0, s44, 0x2000
	s_nop 0
	global_load_lds_dwordx4 v[128:129], off
	s_waitcnt vmcnt(6)
	s_cmp_eq_u32 s57, 10
	s_cbranch_scc0 .Ler_1894_skip
	s_lshl_b32 s84, s36, 19
	s_lshl_b32 s85, s38, 9
	s_add_u32 s84, s84, s85
	s_add_u32 s84, s16, s84
	s_addc_u32 s85, s17, 0
	v_lshlrev_b32_e32 v236, 11, v186
	v_lshl_add_u32 v236, v188, 1, v236
	global_load_dwordx4 v[224:227], v236, s[84:85]
	global_load_dwordx4 v[228:231], v236, s[84:85] offset:256
	s_add_u32 s86, s84, 0x8000
	s_addc_u32 s87, s85, 0
	global_load_dwordx4 v[232:235], v236, s[86:87]
	global_load_dwordx4 v[240:243], v236, s[86:87] offset:256
	s_add_u32 s86, s84, 0x10000
	s_addc_u32 s87, s85, 0
	global_load_dwordx4 v[244:247], v236, s[86:87]
	global_load_dwordx4 v[248:251], v236, s[86:87] offset:256
	s_add_u32 s86, s84, 0x18000
	s_addc_u32 s87, s85, 0
	global_load_dwordx4 v[252:255], v236, s[86:87]
.Ler_1894_skip:
	s_barrier
	s_setprio 1
	v_mfma_f32_16x16x32_bf16 v[52:55], v[200:203], v[144:147], v[52:55]
	v_mfma_f32_16x16x32_bf16 v[48:51], v[210:213], v[144:147], v[48:51]
	v_mfma_f32_16x16x32_bf16 v[36:39], v[200:203], v[168:171], v[36:39]
	v_mfma_f32_16x16x32_bf16 v[32:35], v[210:213], v[168:171], v[32:35]
	v_mfma_f32_16x16x32_bf16 v[20:23], v[200:203], v[176:179], v[20:23]
	v_mfma_f32_16x16x32_bf16 v[16:19], v[210:213], v[176:179], v[16:19]
	v_mfma_f32_16x16x32_bf16 v[4:7], v[200:203], v[192:195], v[4:7]
	v_mfma_f32_16x16x32_bf16 v[0:3], v[210:213], v[192:195], v[0:3]
	v_mfma_f32_16x16x32_bf16 v[52:55], v[206:209], v[148:151], v[52:55]
	v_mfma_f32_16x16x32_bf16 v[48:51], v[214:217], v[148:151], v[48:51]
	v_mfma_f32_16x16x32_bf16 v[36:39], v[206:209], v[172:175], v[36:39]
	v_mfma_f32_16x16x32_bf16 v[32:35], v[214:217], v[172:175], v[32:35]
	v_mfma_f32_16x16x32_bf16 v[20:23], v[206:209], v[180:183], v[20:23]
	v_mfma_f32_16x16x32_bf16 v[16:19], v[214:217], v[180:183], v[16:19]
	v_mfma_f32_16x16x32_bf16 v[4:7], v[206:209], v[196:199], v[4:7]
	v_mfma_f32_16x16x32_bf16 v[0:3], v[214:217], v[196:199], v[0:3]
	s_setprio 0
	s_add_i32 s57, s57, 2
	s_add_u32 s40, s40, 0x100
	s_addc_u32 s41, s41, 0
	s_add_u32 s55, s55, 0x100
	s_addc_u32 s56, s56, 0
	s_cmp_gt_u32 s57, 13
	s_barrier
	s_cbranch_scc0 .LBB0_1894
	v_lshl_or_b32 v168, s38, 8, v188
	v_lshl_add_u32 v170, s36, 8, v186
	v_ashrrev_i32_e32 v169, 31, v168
	v_lshlrev_b64 v[202:203], 1, v[168:169]
	v_ashrrev_i32_e32 v171, 31, v170
	v_or_b32_e32 v182, 16, v170
	v_lshl_add_u64 v[172:173], s[16:17], 0, v[202:203]
	v_lshlrev_b64 v[206:207], 11, v[170:171]
	v_ashrrev_i32_e32 v183, 31, v182
	v_or_b32_e32 v178, 32, v170
	v_lshl_add_u64 v[128:129], v[172:173], 0, v[206:207]
	v_lshlrev_b64 v[184:185], 11, v[182:183]
	v_ashrrev_i32_e32 v179, 31, v178
	v_or_b32_e32 v174, 48, v170
	v_mov_b32_e32 v194, v224
	v_mov_b32_e32 v195, v225
	v_mov_b32_e32 v196, v226
	v_mov_b32_e32 v197, v227
	v_mov_b32_e32 v198, v228
	v_mov_b32_e32 v199, v229
	v_mov_b32_e32 v200, v230
	v_mov_b32_e32 v201, v231
	v_lshl_add_u64 v[128:129], v[172:173], 0, v[184:185]
	v_lshlrev_b64 v[180:181], 11, v[178:179]
	v_ashrrev_i32_e32 v175, 31, v174
	v_mov_b32_e32 v148, v232
	v_mov_b32_e32 v149, v233
	v_mov_b32_e32 v150, v234
	v_mov_b32_e32 v151, v235
	v_mov_b32_e32 v144, v240
	v_mov_b32_e32 v145, v241
	v_mov_b32_e32 v146, v242
	v_mov_b32_e32 v147, v243
	v_lshl_add_u64 v[128:129], v[172:173], 0, v[180:181]
	v_lshlrev_b64 v[176:177], 11, v[174:175]
	v_mov_b32_e32 v140, v244
	v_mov_b32_e32 v141, v245
	v_mov_b32_e32 v142, v246
	v_mov_b32_e32 v143, v247
	v_mov_b32_e32 v136, v248
	v_mov_b32_e32 v137, v249
	v_mov_b32_e32 v138, v250
	v_mov_b32_e32 v139, v251
	v_lshl_add_u64 v[128:129], v[172:173], 0, v[176:177]
	v_mov_b32_e32 v132, v252
	v_mov_b32_e32 v133, v253
	v_mov_b32_e32 v134, v254
	v_mov_b32_e32 v135, v255
	s_nop 0
	global_load_dwordx4 v[128:131], v[128:129], off offset:256
	v_and_b32_e32 v193, 64, v205
	v_xor_b32_e32 v192, 16, v205
	v_add_u32_e32 v208, 64, v193
	v_cmp_lt_i32_e32 vcc, v192, v208
	s_nop 1
	v_cndmask_b32_e32 v192, v205, v192, vcc
	v_lshlrev_b32_e32 v193, 2, v192
	v_xor_b32_e32 v192, 32, v205
	v_cmp_lt_i32_e32 vcc, v192, v208
	s_nop 1
	v_cndmask_b32_e32 v192, v205, v192, vcc
	v_lshlrev_b32_e32 v192, 2, v192
	v_add_u32_e32 v236, 0x80, v170
	v_ashrrev_i32_e32 v237, 31, v236
	v_lshlrev_b64 v[236:237], 11, v[236:237]
	v_lshl_add_u64 v[236:237], v[172:173], 0, v[236:237]
	global_load_dwordx4 v[224:227], v[236:237], off
	global_load_dwordx4 v[228:231], v[236:237], off offset:256
	v_add_u32_e32 v236, 0x90, v170
	v_ashrrev_i32_e32 v237, 31, v236
	v_lshlrev_b64 v[236:237], 11, v[236:237]
	v_lshl_add_u64 v[236:237], v[172:173], 0, v[236:237]
	global_load_dwordx4 v[232:235], v[236:237], off
	global_load_dwordx4 v[240:243], v[236:237], off offset:256
	v_add_u32_e32 v236, 0xa0, v170
	v_ashrrev_i32_e32 v237, 31, v236
	v_lshlrev_b64 v[236:237], 11, v[236:237]
	v_lshl_add_u64 v[236:237], v[172:173], 0, v[236:237]
	global_load_dwordx4 v[244:247], v[236:237], off
	global_load_dwordx4 v[248:251], v[236:237], off offset:256
	v_add_u32_e32 v236, 0xb0, v170
	v_ashrrev_i32_e32 v237, 31, v236
	v_lshlrev_b64 v[236:237], 11, v[236:237]
	v_lshl_add_u64 v[236:237], v[172:173], 0, v[236:237]
	global_load_dwordx4 v[252:255], v[236:237], off
	s_waitcnt vmcnt(24)
	v_lshlrev_b32_e32 v208, 16, v194
	v_and_b32_e32 v209, 0xffff0000, v194
	v_lshlrev_b32_e32 v194, 16, v195
	v_and_b32_e32 v195, 0xffff0000, v195
	v_lshlrev_b32_e32 v210, 16, v196
	v_and_b32_e32 v211, 0xffff0000, v196
	v_lshlrev_b32_e32 v196, 16, v197
	v_and_b32_e32 v197, 0xffff0000, v197
	v_pk_add_f32 v[126:127], v[126:127], v[194:195]
	v_pk_add_f32 v[194:195], v[122:123], v[196:197]
	v_pk_add_f32 v[196:197], v[120:121], v[210:211]
	v_pk_add_f32 v[124:125], v[124:125], v[208:209]
	v_cvt_pk_bf16_f32 v122, v196, v197
	v_mul_f32_e32 v196, v196, v196
	v_cvt_pk_bf16_f32 v120, v124, v125
	v_fmac_f32_e32 v196, v124, v124
	v_mul_f32_e32 v124, v197, v197
	v_fmac_f32_e32 v124, v125, v125
	v_mul_f32_e32 v125, v194, v194
	v_add_f32_e32 v124, v196, v124
	v_fmac_f32_e32 v125, v126, v126
	v_add_f32_e32 v124, v125, v124
	v_mul_f32_e32 v125, v195, v195
	v_cvt_pk_bf16_f32 v121, v126, v127
	v_cvt_pk_bf16_f32 v123, v194, v195
	v_fmac_f32_e32 v125, v127, v127
	v_lshlrev_b32_e32 v126, 16, v199
	v_and_b32_e32 v127, 0xffff0000, v199
	v_lshlrev_b32_e32 v194, 16, v200
	v_and_b32_e32 v195, 0xffff0000, v200
	v_add_f32_e32 v208, v125, v124
	v_lshlrev_b32_e32 v124, 16, v198
	v_and_b32_e32 v125, 0xffff0000, v198
	v_pk_add_f32 v[118:119], v[118:119], v[126:127]
	v_pk_add_f32 v[126:127], v[112:113], v[194:195]
	v_pk_add_f32 v[116:117], v[116:117], v[124:125]
	v_mul_f32_e32 v112, v126, v126
	v_lshlrev_b32_e32 v196, 16, v201
	v_and_b32_e32 v197, 0xffff0000, v201
	v_fmac_f32_e32 v112, v116, v116
	v_mul_f32_e32 v113, v127, v127
	v_pk_add_f32 v[124:125], v[114:115], v[196:197]
	v_add_f32_e32 v112, v112, v208
	v_fmac_f32_e32 v113, v117, v117
	v_add_f32_e32 v112, v113, v112
	v_mul_f32_e32 v113, v124, v124
	v_fmac_f32_e32 v113, v118, v118
	v_add_f32_e32 v112, v113, v112
	v_mul_f32_e32 v113, v125, v125
	v_fmac_f32_e32 v113, v119, v119
	v_add_f32_e32 v115, v113, v112
	ds_bpermute_b32 v196, v193, v115
	v_lshl_add_u64 v[112:113], s[16:17], 0, v[206:207]
	v_lshl_add_u64 v[194:195], v[112:113], 0, v[202:203]
	v_cvt_pk_bf16_f32 v114, v116, v117
	v_cvt_pk_bf16_f32 v116, v126, v127
	s_waitcnt lgkmcnt(0)
	v_add_f32_e32 v112, v115, v196
	ds_bpermute_b32 v113, v192, v112
	v_cvt_pk_bf16_f32 v115, v118, v119
	v_cvt_pk_bf16_f32 v117, v124, v125
	global_store_dwordx4 v[194:195], v[120:123], off
	global_store_dwordx4 v[194:195], v[114:117], off offset:256
	s_and_saveexec_b64 s[36:37], s[8:9]
	s_cbranch_execz .LBB0_1897
	s_waitcnt lgkmcnt(0)
	v_add_f32_e32 v112, v112, v113
	v_mul_f32_e32 v112, 0x4b800000, v112
	v_trunc_f32_e32 v112, v112
	v_mul_f32_e32 v113, 0x2f800000, v112
	v_floor_f32_e32 v113, v113
	v_fmac_f32_e32 v112, 0xcf800000, v113
	v_cvt_u32_f32_e32 v112, v112
	v_cvt_u32_f32_e32 v113, v113
	v_lshl_add_u64 v[114:115], v[170:171], 3, s[18:19]
	global_atomic_add_x2 v[114:115], v[112:113], off

.LBB0_1901:
	s_or_b64 exec, exec, s[36:37]
	v_lshlrev_b32_e32 v82, 16, v133
	v_and_b32_e32 v83, 0xffff0000, v133
	v_lshlrev_b32_e32 v84, 16, v134
	v_and_b32_e32 v85, 0xffff0000, v134
	v_lshlrev_b32_e32 v80, 16, v132
	s_waitcnt lgkmcnt(0)
	v_and_b32_e32 v81, 0xffff0000, v132
	v_lshlrev_b32_e32 v86, 16, v135
	v_and_b32_e32 v87, 0xffff0000, v135
	v_pk_add_f32 v[78:79], v[78:79], v[82:83]
	v_pk_add_f32 v[82:83], v[72:73], v[84:85]
	v_pk_add_f32 v[76:77], v[76:77], v[80:81]
	v_pk_add_f32 v[80:81], v[74:75], v[86:87]
	v_cvt_pk_bf16_f32 v74, v82, v83
	v_mul_f32_e32 v82, v82, v82
	v_cvt_pk_bf16_f32 v72, v76, v77
	v_fmac_f32_e32 v82, v76, v76
	v_mul_f32_e32 v76, v83, v83
	v_fmac_f32_e32 v76, v77, v77
	v_mul_f32_e32 v77, v80, v80
	v_add_f32_e32 v76, v82, v76
	v_fmac_f32_e32 v77, v78, v78
	v_add_f32_e32 v76, v77, v76
	v_mul_f32_e32 v77, v81, v81
	v_cvt_pk_bf16_f32 v73, v78, v79
	v_cvt_pk_bf16_f32 v75, v80, v81
	v_fmac_f32_e32 v77, v79, v79
	s_waitcnt vmcnt(13)
	v_lshlrev_b32_e32 v78, 16, v129
	v_and_b32_e32 v79, 0xffff0000, v129
	v_lshlrev_b32_e32 v80, 16, v130
	v_and_b32_e32 v81, 0xffff0000, v130
	v_add_f32_e32 v84, v77, v76
	v_lshlrev_b32_e32 v76, 16, v128
	v_and_b32_e32 v77, 0xffff0000, v128
	v_pk_add_f32 v[70:71], v[70:71], v[78:79]
	v_pk_add_f32 v[78:79], v[64:65], v[80:81]
	v_pk_add_f32 v[68:69], v[68:69], v[76:77]
	v_mul_f32_e32 v64, v78, v78
	v_lshlrev_b32_e32 v82, 16, v131
	v_and_b32_e32 v83, 0xffff0000, v131
	v_fmac_f32_e32 v64, v68, v68
	v_mul_f32_e32 v65, v79, v79
	v_pk_add_f32 v[76:77], v[66:67], v[82:83]
	v_add_f32_e32 v64, v64, v84
	v_fmac_f32_e32 v65, v69, v69
	v_add_f32_e32 v64, v65, v64
	v_mul_f32_e32 v65, v76, v76
	v_fmac_f32_e32 v65, v70, v70
	v_add_f32_e32 v64, v65, v64
	v_mul_f32_e32 v65, v77, v77
	v_fmac_f32_e32 v65, v71, v71
	v_add_f32_e32 v67, v65, v64
	ds_bpermute_b32 v82, v193, v67
	v_lshl_add_u64 v[64:65], s[16:17], 0, v[176:177]
	v_lshl_add_u64 v[80:81], v[168:169], 1, v[64:65]
	v_cvt_pk_bf16_f32 v66, v68, v69
	v_cvt_pk_bf16_f32 v68, v78, v79
	s_waitcnt lgkmcnt(0)
	v_add_f32_e32 v64, v67, v82
	ds_bpermute_b32 v65, v192, v64
	v_cvt_pk_bf16_f32 v67, v70, v71
	v_cvt_pk_bf16_f32 v69, v76, v77
	global_store_dwordx4 v[80:81], v[72:75], off
	global_store_dwordx4 v[80:81], v[66:69], off offset:256
	s_and_saveexec_b64 s[36:37], s[8:9]
	s_cbranch_execz .LBB0_1903
	s_waitcnt lgkmcnt(0)
	v_add_f32_e32 v64, v64, v65
	v_mul_f32_e32 v64, 0x4b800000, v64
	v_trunc_f32_e32 v64, v64
	v_mul_f32_e32 v65, 0x2f800000, v64
	v_floor_f32_e32 v65, v65
	v_fmac_f32_e32 v64, 0xcf800000, v65
	v_cvt_u32_f32_e32 v64, v64
	v_cvt_u32_f32_e32 v65, v65
	v_lshl_add_u64 v[66:67], v[174:175], 3, s[18:19]
	global_atomic_add_x2 v[66:67], v[64:65], off

.LBB0_2056:
	ds_read_b128 v[128:131], v189
	ds_read_b128 v[132:135], v189 offset:1024
	ds_read_b128 v[136:139], v189 offset:2048
	ds_read_b128 v[140:143], v189 offset:3072
	s_add_u32 s36, s34, 0xfff00080
	s_addc_u32 s37, s35, -1
	s_cmp_eq_u32 s53, 60
	s_cselect_b32 s39, s19, s37
	s_cselect_b32 s38, s29, s36
	s_cselect_b32 s37, s17, s52
	s_cselect_b32 s36, s50, s51
	v_lshl_add_u64 v[184:185], s[34:35], 0, v[160:161]
	s_add_i32 m0, s31, 0xc000
	ds_read_b128 v[144:147], v190
	ds_read_b128 v[148:151], v190 offset:1024
	ds_read_b128 v[168:171], v190 offset:2048
	ds_read_b128 v[172:175], v190 offset:3072
	ds_read_b128 v[176:179], v190 offset:4096
	ds_read_b128 v[180:183], v190 offset:5120
	ds_read_b128 v[192:195], v190 offset:6144
	ds_read_b128 v[196:199], v190 offset:7168
	global_load_lds_dwordx4 v[184:185], off
	v_lshl_add_u64 v[184:185], s[34:35], 0, v[162:163]
	s_add_i32 m0, s31, 0xe000
	s_nop 0
	global_load_lds_dwordx4 v[184:185], off
	s_waitcnt lgkmcnt(8)
	s_barrier
	s_waitcnt lgkmcnt(0)
	s_setprio 1
	s_waitcnt lgkmcnt(0)
	v_mfma_f32_16x16x32_bf16 v[124:127], v[128:131], v[144:147], v[124:127]
	v_mfma_f32_16x16x32_bf16 v[120:123], v[136:139], v[144:147], v[120:123]
	v_mfma_f32_16x16x32_bf16 v[108:111], v[128:131], v[168:171], v[108:111]
	v_mfma_f32_16x16x32_bf16 v[104:107], v[136:139], v[168:171], v[104:107]
	v_mfma_f32_16x16x32_bf16 v[92:95], v[128:131], v[176:179], v[92:95]
	v_mfma_f32_16x16x32_bf16 v[88:91], v[136:139], v[176:179], v[88:91]
	v_mfma_f32_16x16x32_bf16 v[76:79], v[128:131], v[192:195], v[76:79]
	v_mfma_f32_16x16x32_bf16 v[72:75], v[136:139], v[192:195], v[72:75]
	v_mfma_f32_16x16x32_bf16 v[124:127], v[132:135], v[148:151], v[124:127]
	v_mfma_f32_16x16x32_bf16 v[120:123], v[140:143], v[148:151], v[120:123]
	v_mfma_f32_16x16x32_bf16 v[108:111], v[132:135], v[172:175], v[108:111]
	v_mfma_f32_16x16x32_bf16 v[104:107], v[140:143], v[172:175], v[104:107]
	v_mfma_f32_16x16x32_bf16 v[92:95], v[132:135], v[180:183], v[92:95]
	v_mfma_f32_16x16x32_bf16 v[88:91], v[140:143], v[180:183], v[88:91]
	v_mfma_f32_16x16x32_bf16 v[76:79], v[132:135], v[196:199], v[76:79]
	v_mfma_f32_16x16x32_bf16 v[72:75], v[140:143], v[196:199], v[72:75]
	s_setprio 0
	s_barrier
	s_add_i32 s54, s48, s21
	v_lshl_add_u64 v[184:185], s[36:37], 0, v[154:155]
	s_mov_b32 m0, s54
	ds_read_b128 v[200:203], v191
	ds_read_b128 v[206:209], v191 offset:1024
	ds_read_b128 v[210:213], v191 offset:2048
	ds_read_b128 v[214:217], v191 offset:3072
	global_load_lds_dwordx4 v[184:185], off
	v_lshl_add_u64 v[218:219], s[36:37], 0, v[158:159]
	s_add_i32 m0, s54, 0x2000
	s_nop 0
	global_load_lds_dwordx4 v[218:219], off
	s_barrier
	s_waitcnt lgkmcnt(0)
	s_setprio 1
	s_waitcnt lgkmcnt(0)
	v_mfma_f32_16x16x32_bf16 v[116:119], v[200:203], v[144:147], v[116:119]
	v_mfma_f32_16x16x32_bf16 v[112:115], v[210:213], v[144:147], v[112:115]
	v_mfma_f32_16x16x32_bf16 v[100:103], v[200:203], v[168:171], v[100:103]
	v_mfma_f32_16x16x32_bf16 v[96:99], v[210:213], v[168:171], v[96:99]
	v_mfma_f32_16x16x32_bf16 v[84:87], v[200:203], v[176:179], v[84:87]
	v_mfma_f32_16x16x32_bf16 v[80:83], v[210:213], v[176:179], v[80:83]
	v_mfma_f32_16x16x32_bf16 v[68:71], v[200:203], v[192:195], v[68:71]
	v_mfma_f32_16x16x32_bf16 v[64:67], v[210:213], v[192:195], v[64:67]
	v_mfma_f32_16x16x32_bf16 v[116:119], v[206:209], v[148:151], v[116:119]
	v_mfma_f32_16x16x32_bf16 v[112:115], v[214:217], v[148:151], v[112:115]
	v_mfma_f32_16x16x32_bf16 v[100:103], v[206:209], v[172:175], v[100:103]
	v_mfma_f32_16x16x32_bf16 v[96:99], v[214:217], v[172:175], v[96:99]
	v_mfma_f32_16x16x32_bf16 v[84:87], v[206:209], v[180:183], v[84:87]
	v_mfma_f32_16x16x32_bf16 v[80:83], v[214:217], v[180:183], v[80:83]
	v_mfma_f32_16x16x32_bf16 v[68:71], v[206:209], v[196:199], v[68:71]
	v_mfma_f32_16x16x32_bf16 v[64:67], v[214:217], v[196:199], v[64:67]
	s_setprio 0
	s_mov_b32 m0, s31
	v_lshl_add_u64 v[220:221], s[38:39], 0, v[152:153]
	s_barrier
	ds_read_b128 v[144:147], v190 offset:16384
	ds_read_b128 v[148:151], v190 offset:17408
	ds_read_b128 v[168:171], v190 offset:18432
	ds_read_b128 v[172:175], v190 offset:19456
	ds_read_b128 v[176:179], v190 offset:20480
	ds_read_b128 v[180:183], v190 offset:21504
	ds_read_b128 v[192:195], v190 offset:22528
	ds_read_b128 v[196:199], v190 offset:23552
	global_load_lds_dwordx4 v[220:221], off
	v_lshl_add_u64 v[222:223], s[38:39], 0, v[156:157]
	s_mov_b32 m0, s33
	s_nop 0
	global_load_lds_dwordx4 v[222:223], off
	s_barrier
	s_waitcnt lgkmcnt(0)
	s_setprio 1
	s_waitcnt lgkmcnt(0)
	v_mfma_f32_16x16x32_bf16 v[60:63], v[128:131], v[144:147], v[60:63]
	v_mfma_f32_16x16x32_bf16 v[56:59], v[136:139], v[144:147], v[56:59]
	v_mfma_f32_16x16x32_bf16 v[44:47], v[128:131], v[168:171], v[44:47]
	v_mfma_f32_16x16x32_bf16 v[40:43], v[136:139], v[168:171], v[40:43]
	v_mfma_f32_16x16x32_bf16 v[28:31], v[128:131], v[176:179], v[28:31]
	v_mfma_f32_16x16x32_bf16 v[24:27], v[136:139], v[176:179], v[24:27]
	v_mfma_f32_16x16x32_bf16 v[12:15], v[128:131], v[192:195], v[12:15]
	v_mfma_f32_16x16x32_bf16 v[8:11], v[136:139], v[192:195], v[8:11]
	v_mfma_f32_16x16x32_bf16 v[60:63], v[132:135], v[148:151], v[60:63]
	v_mfma_f32_16x16x32_bf16 v[56:59], v[140:143], v[148:151], v[56:59]
	v_mfma_f32_16x16x32_bf16 v[44:47], v[132:135], v[172:175], v[44:47]
	v_mfma_f32_16x16x32_bf16 v[40:43], v[140:143], v[172:175], v[40:43]
	v_mfma_f32_16x16x32_bf16 v[28:31], v[132:135], v[180:183], v[28:31]
	v_mfma_f32_16x16x32_bf16 v[24:27], v[140:143], v[180:183], v[24:27]
	v_mfma_f32_16x16x32_bf16 v[12:15], v[132:135], v[196:199], v[12:15]
	v_mfma_f32_16x16x32_bf16 v[8:11], v[140:143], v[196:199], v[8:11]
	s_setprio 0
	s_barrier
	s_add_u32 s54, s36, 0x100000
	s_addc_u32 s55, s37, 0
	s_add_i32 s56, s49, s21
	v_lshl_add_u64 v[128:129], s[54:55], 0, v[154:155]
	s_mov_b32 m0, s56
	s_nop 0
	global_load_lds_dwordx4 v[128:129], off
	v_lshl_add_u64 v[128:129], s[54:55], 0, v[158:159]
	s_add_i32 m0, s56, 0x2000
	s_nop 0
	global_load_lds_dwordx4 v[128:129], off
	s_waitcnt vmcnt(6)
	s_barrier
	s_setprio 1
	v_mfma_f32_16x16x32_bf16 v[52:55], v[200:203], v[144:147], v[52:55]
	v_mfma_f32_16x16x32_bf16 v[48:51], v[210:213], v[144:147], v[48:51]
	v_mfma_f32_16x16x32_bf16 v[36:39], v[200:203], v[168:171], v[36:39]
	v_mfma_f32_16x16x32_bf16 v[32:35], v[210:213], v[168:171], v[32:35]
	v_mfma_f32_16x16x32_bf16 v[20:23], v[200:203], v[176:179], v[20:23]
	v_mfma_f32_16x16x32_bf16 v[16:19], v[210:213], v[176:179], v[16:19]
	v_mfma_f32_16x16x32_bf16 v[4:7], v[200:203], v[192:195], v[4:7]
	v_mfma_f32_16x16x32_bf16 v[0:3], v[210:213], v[192:195], v[0:3]
	v_mfma_f32_16x16x32_bf16 v[52:55], v[206:209], v[148:151], v[52:55]
	v_mfma_f32_16x16x32_bf16 v[48:51], v[214:217], v[148:151], v[48:51]
	v_mfma_f32_16x16x32_bf16 v[36:39], v[206:209], v[172:175], v[36:39]
	v_mfma_f32_16x16x32_bf16 v[32:35], v[214:217], v[172:175], v[32:35]
	v_mfma_f32_16x16x32_bf16 v[20:23], v[206:209], v[180:183], v[20:23]
	v_mfma_f32_16x16x32_bf16 v[16:19], v[214:217], v[180:183], v[16:19]
	v_mfma_f32_16x16x32_bf16 v[4:7], v[206:209], v[196:199], v[4:7]
	v_mfma_f32_16x16x32_bf16 v[0:3], v[214:217], v[196:199], v[0:3]
	s_setprio 0
	s_add_i32 s54, 0, 0x18000
	v_add_u32_e32 v140, s54, v187
	s_barrier
	ds_read_b128 v[128:131], v140
	ds_read_b128 v[132:135], v140 offset:1024
	ds_read_b128 v[136:139], v140 offset:2048
	ds_read_b128 v[140:143], v140 offset:3072
	s_add_u32 s38, s38, 0x100000
	s_addc_u32 s39, s39, 0
	s_mov_b32 m0, s40
	v_lshl_add_u64 v[200:201], s[38:39], 0, v[152:153]
	ds_read_b128 v[144:147], v190 offset:32768
	ds_read_b128 v[148:151], v190 offset:33792
	ds_read_b128 v[168:171], v190 offset:34816
	ds_read_b128 v[172:175], v190 offset:35840
	ds_read_b128 v[176:179], v190 offset:36864
	ds_read_b128 v[180:183], v190 offset:37888
	ds_read_b128 v[192:195], v190 offset:38912
	ds_read_b128 v[196:199], v190 offset:39936
	global_load_lds_dwordx4 v[200:201], off
	v_lshl_add_u64 v[200:201], s[38:39], 0, v[156:157]
	s_mov_b32 m0, s41
	s_nop 0
	global_load_lds_dwordx4 v[200:201], off
	s_waitcnt lgkmcnt(8)
	s_barrier
	s_waitcnt lgkmcnt(0)
	s_setprio 1
	s_waitcnt lgkmcnt(0)
	v_mfma_f32_16x16x32_bf16 v[124:127], v[128:131], v[144:147], v[124:127]
	v_mfma_f32_16x16x32_bf16 v[120:123], v[136:139], v[144:147], v[120:123]
	v_mfma_f32_16x16x32_bf16 v[108:111], v[128:131], v[168:171], v[108:111]
	v_mfma_f32_16x16x32_bf16 v[104:107], v[136:139], v[168:171], v[104:107]
	v_mfma_f32_16x16x32_bf16 v[92:95], v[128:131], v[176:179], v[92:95]
	v_mfma_f32_16x16x32_bf16 v[88:91], v[136:139], v[176:179], v[88:91]
	v_mfma_f32_16x16x32_bf16 v[76:79], v[128:131], v[192:195], v[76:79]
	v_mfma_f32_16x16x32_bf16 v[72:75], v[136:139], v[192:195], v[72:75]
	v_mfma_f32_16x16x32_bf16 v[124:127], v[132:135], v[148:151], v[124:127]
	v_mfma_f32_16x16x32_bf16 v[120:123], v[140:143], v[148:151], v[120:123]
	v_mfma_f32_16x16x32_bf16 v[108:111], v[132:135], v[172:175], v[108:111]
	v_mfma_f32_16x16x32_bf16 v[104:107], v[140:143], v[172:175], v[104:107]
	v_mfma_f32_16x16x32_bf16 v[92:95], v[132:135], v[180:183], v[92:95]
	v_mfma_f32_16x16x32_bf16 v[88:91], v[140:143], v[180:183], v[88:91]
	v_mfma_f32_16x16x32_bf16 v[76:79], v[132:135], v[196:199], v[76:79]
	v_mfma_f32_16x16x32_bf16 v[72:75], v[140:143], v[196:199], v[72:75]
	s_setprio 0
	s_barrier
	s_add_i32 s38, 0, 0x1c000
	s_add_i32 s39, s54, s21
	v_add_u32_e32 v214, s38, v187
	v_lshl_add_u64 v[184:185], v[184:185], 0, s[14:15]
	s_mov_b32 m0, s39
	ds_read_b128 v[200:203], v214
	ds_read_b128 v[206:209], v214 offset:1024
	ds_read_b128 v[210:213], v214 offset:2048
	ds_read_b128 v[214:217], v214 offset:3072
	global_load_lds_dwordx4 v[184:185], off
	v_lshl_add_u64 v[184:185], v[218:219], 0, s[14:15]
	s_add_i32 m0, s39, 0x2000
	s_nop 0
	global_load_lds_dwordx4 v[184:185], off
	s_barrier
	s_waitcnt lgkmcnt(0)
	s_setprio 1
	s_waitcnt lgkmcnt(0)
	v_mfma_f32_16x16x32_bf16 v[116:119], v[200:203], v[144:147], v[116:119]
	v_mfma_f32_16x16x32_bf16 v[112:115], v[210:213], v[144:147], v[112:115]
	v_mfma_f32_16x16x32_bf16 v[100:103], v[200:203], v[168:171], v[100:103]
	v_mfma_f32_16x16x32_bf16 v[96:99], v[210:213], v[168:171], v[96:99]
	v_mfma_f32_16x16x32_bf16 v[84:87], v[200:203], v[176:179], v[84:87]
	v_mfma_f32_16x16x32_bf16 v[80:83], v[210:213], v[176:179], v[80:83]
	v_mfma_f32_16x16x32_bf16 v[68:71], v[200:203], v[192:195], v[68:71]
	v_mfma_f32_16x16x32_bf16 v[64:67], v[210:213], v[192:195], v[64:67]
	v_mfma_f32_16x16x32_bf16 v[116:119], v[206:209], v[148:151], v[116:119]
	v_mfma_f32_16x16x32_bf16 v[112:115], v[214:217], v[148:151], v[112:115]
	v_mfma_f32_16x16x32_bf16 v[100:103], v[206:209], v[172:175], v[100:103]
	v_mfma_f32_16x16x32_bf16 v[96:99], v[214:217], v[172:175], v[96:99]
	v_mfma_f32_16x16x32_bf16 v[84:87], v[206:209], v[180:183], v[84:87]
	v_mfma_f32_16x16x32_bf16 v[80:83], v[214:217], v[180:183], v[80:83]
	v_mfma_f32_16x16x32_bf16 v[68:71], v[206:209], v[196:199], v[68:71]
	v_mfma_f32_16x16x32_bf16 v[64:67], v[214:217], v[196:199], v[64:67]
	s_setprio 0
	s_mov_b32 m0, s43
	v_lshl_add_u64 v[184:185], v[220:221], 0, s[14:15]
	s_barrier
	ds_read_b128 v[144:147], v190 offset:49152
	ds_read_b128 v[148:151], v190 offset:50176
	ds_read_b128 v[168:171], v190 offset:51200
	ds_read_b128 v[172:175], v190 offset:52224
	ds_read_b128 v[176:179], v190 offset:53248
	ds_read_b128 v[180:183], v190 offset:54272
	ds_read_b128 v[192:195], v190 offset:55296
	ds_read_b128 v[196:199], v190 offset:56320
	global_load_lds_dwordx4 v[184:185], off
	v_lshl_add_u64 v[184:185], v[222:223], 0, s[14:15]
	s_mov_b32 m0, s44
	s_nop 0
	global_load_lds_dwordx4 v[184:185], off
	s_barrier
	s_waitcnt lgkmcnt(0)
	s_setprio 1
	s_waitcnt lgkmcnt(0)
	v_mfma_f32_16x16x32_bf16 v[60:63], v[128:131], v[144:147], v[60:63]
	v_mfma_f32_16x16x32_bf16 v[56:59], v[136:139], v[144:147], v[56:59]
	v_mfma_f32_16x16x32_bf16 v[44:47], v[128:131], v[168:171], v[44:47]
	v_mfma_f32_16x16x32_bf16 v[40:43], v[136:139], v[168:171], v[40:43]
	v_mfma_f32_16x16x32_bf16 v[28:31], v[128:131], v[176:179], v[28:31]
	v_mfma_f32_16x16x32_bf16 v[24:27], v[136:139], v[176:179], v[24:27]
	v_mfma_f32_16x16x32_bf16 v[12:15], v[128:131], v[192:195], v[12:15]
	v_mfma_f32_16x16x32_bf16 v[8:11], v[136:139], v[192:195], v[8:11]
	v_mfma_f32_16x16x32_bf16 v[60:63], v[132:135], v[148:151], v[60:63]
	v_mfma_f32_16x16x32_bf16 v[56:59], v[140:143], v[148:151], v[56:59]
	v_mfma_f32_16x16x32_bf16 v[44:47], v[132:135], v[172:175], v[44:47]
	v_mfma_f32_16x16x32_bf16 v[40:43], v[140:143], v[172:175], v[40:43]
	v_mfma_f32_16x16x32_bf16 v[28:31], v[132:135], v[180:183], v[28:31]
	v_mfma_f32_16x16x32_bf16 v[24:27], v[140:143], v[180:183], v[24:27]
	v_mfma_f32_16x16x32_bf16 v[12:15], v[132:135], v[196:199], v[12:15]
	v_mfma_f32_16x16x32_bf16 v[8:11], v[140:143], v[196:199], v[8:11]
	s_setprio 0
	s_barrier
	s_add_u32 s36, s36, 0x100080
	s_addc_u32 s37, s37, 0
	s_add_i32 s38, s38, s21
	v_lshl_add_u64 v[128:129], s[36:37], 0, v[154:155]
	s_mov_b32 m0, s38
	s_nop 0
	global_load_lds_dwordx4 v[128:129], off
	v_lshl_add_u64 v[128:129], s[36:37], 0, v[158:159]
	s_add_i32 m0, s38, 0x2000
	s_nop 0
	global_load_lds_dwordx4 v[128:129], off
	s_waitcnt vmcnt(6)
	s_cmp_eq_u32 s53, 58
	s_cbranch_scc0 .Ler_2056_skip
	s_lshl_b32 s84, s28, 19
	s_lshl_b32 s85, s30, 9
	s_add_u32 s84, s84, s85
	s_add_u32 s84, s10, s84
	s_addc_u32 s85, s11, 0
	v_lshlrev_b32_e32 v236, 11, v186
	v_lshl_add_u32 v236, v188, 1, v236
	global_load_dwordx4 v[224:227], v236, s[84:85]
	global_load_dwordx4 v[228:231], v236, s[84:85] offset:256
	s_add_u32 s86, s84, 0x8000
	s_addc_u32 s87, s85, 0
	global_load_dwordx4 v[232:235], v236, s[86:87]
	global_load_dwordx4 v[240:243], v236, s[86:87] offset:256
	s_add_u32 s86, s84, 0x10000
	s_addc_u32 s87, s85, 0
	global_load_dwordx4 v[244:247], v236, s[86:87]
	global_load_dwordx4 v[248:251], v236, s[86:87] offset:256
	s_add_u32 s86, s84, 0x18000
	s_addc_u32 s87, s85, 0
	global_load_dwordx4 v[252:255], v236, s[86:87]
.Ler_2056_skip:
	s_barrier
	s_setprio 1
	v_mfma_f32_16x16x32_bf16 v[52:55], v[200:203], v[144:147], v[52:55]
	v_mfma_f32_16x16x32_bf16 v[48:51], v[210:213], v[144:147], v[48:51]
	v_mfma_f32_16x16x32_bf16 v[36:39], v[200:203], v[168:171], v[36:39]
	v_mfma_f32_16x16x32_bf16 v[32:35], v[210:213], v[168:171], v[32:35]
	v_mfma_f32_16x16x32_bf16 v[20:23], v[200:203], v[176:179], v[20:23]
	v_mfma_f32_16x16x32_bf16 v[16:19], v[210:213], v[176:179], v[16:19]
	v_mfma_f32_16x16x32_bf16 v[4:7], v[200:203], v[192:195], v[4:7]
	v_mfma_f32_16x16x32_bf16 v[0:3], v[210:213], v[192:195], v[0:3]
	v_mfma_f32_16x16x32_bf16 v[52:55], v[206:209], v[148:151], v[52:55]
	v_mfma_f32_16x16x32_bf16 v[48:51], v[214:217], v[148:151], v[48:51]
	v_mfma_f32_16x16x32_bf16 v[36:39], v[206:209], v[172:175], v[36:39]
	v_mfma_f32_16x16x32_bf16 v[32:35], v[214:217], v[172:175], v[32:35]
	v_mfma_f32_16x16x32_bf16 v[20:23], v[206:209], v[180:183], v[20:23]
	v_mfma_f32_16x16x32_bf16 v[16:19], v[214:217], v[180:183], v[16:19]
	v_mfma_f32_16x16x32_bf16 v[4:7], v[206:209], v[196:199], v[4:7]
	v_mfma_f32_16x16x32_bf16 v[0:3], v[214:217], v[196:199], v[0:3]
	s_setprio 0
	s_add_i32 s53, s53, 2
	s_add_u32 s34, s34, 0x100
	s_addc_u32 s35, s35, 0
	s_add_u32 s51, s51, 0x100
	s_addc_u32 s52, s52, 0
	s_cmp_gt_u32 s53, 61
	s_barrier
	s_cbranch_scc0 .LBB0_2056
	v_lshl_or_b32 v168, s30, 8, v188
	v_lshl_add_u32 v170, s28, 8, v186
	v_ashrrev_i32_e32 v169, 31, v168
	v_lshlrev_b64 v[202:203], 1, v[168:169]
	v_ashrrev_i32_e32 v171, 31, v170
	v_or_b32_e32 v182, 16, v170
	v_lshl_add_u64 v[172:173], s[10:11], 0, v[202:203]
	v_lshlrev_b64 v[206:207], 11, v[170:171]
	v_ashrrev_i32_e32 v183, 31, v182
	v_or_b32_e32 v178, 32, v170
	v_lshl_add_u64 v[128:129], v[172:173], 0, v[206:207]
	v_lshlrev_b64 v[184:185], 11, v[182:183]
	v_ashrrev_i32_e32 v179, 31, v178
	v_or_b32_e32 v174, 48, v170
	v_mov_b32_e32 v194, v224
	v_mov_b32_e32 v195, v225
	v_mov_b32_e32 v196, v226
	v_mov_b32_e32 v197, v227
	v_mov_b32_e32 v198, v228
	v_mov_b32_e32 v199, v229
	v_mov_b32_e32 v200, v230
	v_mov_b32_e32 v201, v231
	v_lshl_add_u64 v[128:129], v[172:173], 0, v[184:185]
	v_lshlrev_b64 v[180:181], 11, v[178:179]
	v_ashrrev_i32_e32 v175, 31, v174
	v_mov_b32_e32 v148, v232
	v_mov_b32_e32 v149, v233
	v_mov_b32_e32 v150, v234
	v_mov_b32_e32 v151, v235
	v_mov_b32_e32 v144, v240
	v_mov_b32_e32 v145, v241
	v_mov_b32_e32 v146, v242
	v_mov_b32_e32 v147, v243
	v_lshl_add_u64 v[128:129], v[172:173], 0, v[180:181]
	v_lshlrev_b64 v[176:177], 11, v[174:175]
	v_mov_b32_e32 v140, v244
	v_mov_b32_e32 v141, v245
	v_mov_b32_e32 v142, v246
	v_mov_b32_e32 v143, v247
	v_mov_b32_e32 v136, v248
	v_mov_b32_e32 v137, v249
	v_mov_b32_e32 v138, v250
	v_mov_b32_e32 v139, v251
	v_lshl_add_u64 v[128:129], v[172:173], 0, v[176:177]
	v_mov_b32_e32 v132, v252
	v_mov_b32_e32 v133, v253
	v_mov_b32_e32 v134, v254
	v_mov_b32_e32 v135, v255
	s_nop 0
	global_load_dwordx4 v[128:131], v[128:129], off offset:256
	v_and_b32_e32 v193, 64, v205
	v_xor_b32_e32 v192, 16, v205
	v_add_u32_e32 v208, 64, v193
	v_cmp_lt_i32_e32 vcc, v192, v208
	s_nop 1
	v_cndmask_b32_e32 v192, v205, v192, vcc
	v_lshlrev_b32_e32 v193, 2, v192
	v_xor_b32_e32 v192, 32, v205
	v_cmp_lt_i32_e32 vcc, v192, v208
	s_nop 1
	v_cndmask_b32_e32 v192, v205, v192, vcc
	v_lshlrev_b32_e32 v192, 2, v192
	v_add_u32_e32 v236, 0x80, v170
	v_ashrrev_i32_e32 v237, 31, v236
	v_lshlrev_b64 v[236:237], 11, v[236:237]
	v_lshl_add_u64 v[236:237], v[172:173], 0, v[236:237]
	global_load_dwordx4 v[224:227], v[236:237], off
	global_load_dwordx4 v[228:231], v[236:237], off offset:256
	v_add_u32_e32 v236, 0x90, v170
	v_ashrrev_i32_e32 v237, 31, v236
	v_lshlrev_b64 v[236:237], 11, v[236:237]
	v_lshl_add_u64 v[236:237], v[172:173], 0, v[236:237]
	global_load_dwordx4 v[232:235], v[236:237], off
	global_load_dwordx4 v[240:243], v[236:237], off offset:256
	v_add_u32_e32 v236, 0xa0, v170
	v_ashrrev_i32_e32 v237, 31, v236
	v_lshlrev_b64 v[236:237], 11, v[236:237]
	v_lshl_add_u64 v[236:237], v[172:173], 0, v[236:237]
	global_load_dwordx4 v[244:247], v[236:237], off
	global_load_dwordx4 v[248:251], v[236:237], off offset:256
	v_add_u32_e32 v236, 0xb0, v170
	v_ashrrev_i32_e32 v237, 31, v236
	v_lshlrev_b64 v[236:237], 11, v[236:237]
	v_lshl_add_u64 v[236:237], v[172:173], 0, v[236:237]
	global_load_dwordx4 v[252:255], v[236:237], off
	s_waitcnt vmcnt(24)
	v_lshlrev_b32_e32 v208, 16, v194
	v_and_b32_e32 v209, 0xffff0000, v194
	v_lshlrev_b32_e32 v194, 16, v195
	v_and_b32_e32 v195, 0xffff0000, v195
	v_lshlrev_b32_e32 v210, 16, v196
	v_and_b32_e32 v211, 0xffff0000, v196
	v_lshlrev_b32_e32 v196, 16, v197
	v_and_b32_e32 v197, 0xffff0000, v197
	v_pk_add_f32 v[126:127], v[126:127], v[194:195]
	v_pk_add_f32 v[194:195], v[122:123], v[196:197]
	v_pk_add_f32 v[196:197], v[120:121], v[210:211]
	v_pk_add_f32 v[124:125], v[124:125], v[208:209]
	v_cvt_pk_bf16_f32 v122, v196, v197
	v_mul_f32_e32 v196, v196, v196
	v_cvt_pk_bf16_f32 v120, v124, v125
	v_fmac_f32_e32 v196, v124, v124
	v_mul_f32_e32 v124, v197, v197
	v_fmac_f32_e32 v124, v125, v125
	v_mul_f32_e32 v125, v194, v194
	v_add_f32_e32 v124, v196, v124
	v_fmac_f32_e32 v125, v126, v126
	v_add_f32_e32 v124, v125, v124
	v_mul_f32_e32 v125, v195, v195
	v_cvt_pk_bf16_f32 v121, v126, v127
	v_cvt_pk_bf16_f32 v123, v194, v195
	v_fmac_f32_e32 v125, v127, v127
	v_lshlrev_b32_e32 v126, 16, v199
	v_and_b32_e32 v127, 0xffff0000, v199
	v_lshlrev_b32_e32 v194, 16, v200
	v_and_b32_e32 v195, 0xffff0000, v200
	v_add_f32_e32 v208, v125, v124
	v_lshlrev_b32_e32 v124, 16, v198
	v_and_b32_e32 v125, 0xffff0000, v198
	v_pk_add_f32 v[118:119], v[118:119], v[126:127]
	v_pk_add_f32 v[126:127], v[112:113], v[194:195]
	v_pk_add_f32 v[116:117], v[116:117], v[124:125]
	v_mul_f32_e32 v112, v126, v126
	v_lshlrev_b32_e32 v196, 16, v201
	v_and_b32_e32 v197, 0xffff0000, v201
	v_fmac_f32_e32 v112, v116, v116
	v_mul_f32_e32 v113, v127, v127
	v_pk_add_f32 v[124:125], v[114:115], v[196:197]
	v_add_f32_e32 v112, v112, v208
	v_fmac_f32_e32 v113, v117, v117
	v_add_f32_e32 v112, v113, v112
	v_mul_f32_e32 v113, v124, v124
	v_fmac_f32_e32 v113, v118, v118
	v_add_f32_e32 v112, v113, v112
	v_mul_f32_e32 v113, v125, v125
	v_fmac_f32_e32 v113, v119, v119
	v_add_f32_e32 v115, v113, v112
	ds_bpermute_b32 v196, v193, v115
	v_lshl_add_u64 v[112:113], s[10:11], 0, v[206:207]
	v_lshl_add_u64 v[194:195], v[112:113], 0, v[202:203]
	v_cvt_pk_bf16_f32 v114, v116, v117
	v_cvt_pk_bf16_f32 v116, v126, v127
	s_waitcnt lgkmcnt(0)
	v_add_f32_e32 v112, v115, v196
	ds_bpermute_b32 v113, v192, v112
	v_cvt_pk_bf16_f32 v115, v118, v119
	v_cvt_pk_bf16_f32 v117, v124, v125
	global_store_dwordx4 v[194:195], v[120:123], off
	global_store_dwordx4 v[194:195], v[114:117], off offset:256
	s_and_saveexec_b64 s[28:29], s[4:5]
	s_cbranch_execz .LBB0_2059
	s_waitcnt lgkmcnt(0)
	v_add_f32_e32 v112, v112, v113
	v_mul_f32_e32 v112, 0x4b800000, v112
	v_trunc_f32_e32 v112, v112
	v_mul_f32_e32 v113, 0x2f800000, v112
	v_floor_f32_e32 v113, v113
	v_fmac_f32_e32 v112, 0xcf800000, v113
	v_cvt_u32_f32_e32 v112, v112
	v_cvt_u32_f32_e32 v113, v113
	v_lshl_add_u64 v[114:115], v[170:171], 3, s[12:13]
	global_atomic_add_x2 v[114:115], v[112:113], off

.LBB0_2063:
	s_or_b64 exec, exec, s[28:29]
	v_lshlrev_b32_e32 v82, 16, v133
	v_and_b32_e32 v83, 0xffff0000, v133
	v_lshlrev_b32_e32 v84, 16, v134
	v_and_b32_e32 v85, 0xffff0000, v134
	v_lshlrev_b32_e32 v80, 16, v132
	s_waitcnt lgkmcnt(0)
	v_and_b32_e32 v81, 0xffff0000, v132
	v_lshlrev_b32_e32 v86, 16, v135
	v_and_b32_e32 v87, 0xffff0000, v135
	v_pk_add_f32 v[78:79], v[78:79], v[82:83]
	v_pk_add_f32 v[82:83], v[72:73], v[84:85]
	v_pk_add_f32 v[76:77], v[76:77], v[80:81]
	v_pk_add_f32 v[80:81], v[74:75], v[86:87]
	v_cvt_pk_bf16_f32 v74, v82, v83
	v_mul_f32_e32 v82, v82, v82
	v_cvt_pk_bf16_f32 v72, v76, v77
	v_fmac_f32_e32 v82, v76, v76
	v_mul_f32_e32 v76, v83, v83
	v_fmac_f32_e32 v76, v77, v77
	v_mul_f32_e32 v77, v80, v80
	v_add_f32_e32 v76, v82, v76
	v_fmac_f32_e32 v77, v78, v78
	v_add_f32_e32 v76, v77, v76
	v_mul_f32_e32 v77, v81, v81
	v_cvt_pk_bf16_f32 v73, v78, v79
	v_cvt_pk_bf16_f32 v75, v80, v81
	v_fmac_f32_e32 v77, v79, v79
	s_waitcnt vmcnt(13)
	v_lshlrev_b32_e32 v78, 16, v129
	v_and_b32_e32 v79, 0xffff0000, v129
	v_lshlrev_b32_e32 v80, 16, v130
	v_and_b32_e32 v81, 0xffff0000, v130
	v_add_f32_e32 v84, v77, v76
	v_lshlrev_b32_e32 v76, 16, v128
	v_and_b32_e32 v77, 0xffff0000, v128
	v_pk_add_f32 v[70:71], v[70:71], v[78:79]
	v_pk_add_f32 v[78:79], v[64:65], v[80:81]
	v_pk_add_f32 v[68:69], v[68:69], v[76:77]
	v_mul_f32_e32 v64, v78, v78
	v_lshlrev_b32_e32 v82, 16, v131
	v_and_b32_e32 v83, 0xffff0000, v131
	v_fmac_f32_e32 v64, v68, v68
	v_mul_f32_e32 v65, v79, v79
	v_pk_add_f32 v[76:77], v[66:67], v[82:83]
	v_add_f32_e32 v64, v64, v84
	v_fmac_f32_e32 v65, v69, v69
	v_add_f32_e32 v64, v65, v64
	v_mul_f32_e32 v65, v76, v76
	v_fmac_f32_e32 v65, v70, v70
	v_add_f32_e32 v64, v65, v64
	v_mul_f32_e32 v65, v77, v77
	v_fmac_f32_e32 v65, v71, v71
	v_add_f32_e32 v67, v65, v64
	ds_bpermute_b32 v82, v193, v67
	v_lshl_add_u64 v[64:65], s[10:11], 0, v[176:177]
	v_lshl_add_u64 v[80:81], v[168:169], 1, v[64:65]
	v_cvt_pk_bf16_f32 v66, v68, v69
	v_cvt_pk_bf16_f32 v68, v78, v79
	s_waitcnt lgkmcnt(0)
	v_add_f32_e32 v64, v67, v82
	ds_bpermute_b32 v65, v192, v64
	v_cvt_pk_bf16_f32 v67, v70, v71
	v_cvt_pk_bf16_f32 v69, v76, v77
	global_store_dwordx4 v[80:81], v[72:75], off
	global_store_dwordx4 v[80:81], v[66:69], off offset:256
	s_and_saveexec_b64 s[28:29], s[4:5]
	s_cbranch_execz .LBB0_2065
	s_waitcnt lgkmcnt(0)
	v_add_f32_e32 v64, v64, v65
	v_mul_f32_e32 v64, 0x4b800000, v64
	v_trunc_f32_e32 v64, v64
	v_mul_f32_e32 v65, 0x2f800000, v64
	v_floor_f32_e32 v65, v65
	v_fmac_f32_e32 v64, 0xcf800000, v65
	v_cvt_u32_f32_e32 v64, v64
	v_cvt_u32_f32_e32 v65, v65
	v_lshl_add_u64 v[66:67], v[174:175], 3, s[12:13]
	global_atomic_add_x2 v[66:67], v[64:65], off
